# FN 13,16: the L1 w_out residual phase also applies the following ffn RMS norm (bf16 H) in its epilogue and the last phase applies the final norm; phases 14 and 17 (and the barrier before the exit) are
# speedup vs baseline: 1.0247x; 1.0078x over previous
; #define GAS __attribute__((address_space(1)))
; template <class T> __device__ __forceinline__ GAS T* gptr(T* q) { return (GAS T*)(unsigned long long)uptr(q); }
; __device__ __forceinline__ void gemm_epilogue(LAS unsigned char* lds, const GD& gd, const f32x4 (&acc)[2][2][4][2], const Unit& u) {
;     ...
;     if (mode == M_RES) {
;         const bool lat = row_u < NL;
;         const int rb = lat ? (row_u >> 12) : 4;
;         GAS const float* gmr = gptr(gd.gm + rb * 6144 + u.pn * BM);
;         GAS const float* xin = gptr((lat ? gd.xin_lat : gd.xin_ctx - (size_t)NL * DM) + (size_t)row_u * DM + u.pn * BM);
;         GAS float* xout = gptr((lat ? gd.xout_lat : gd.xout_ctx - (size_t)NL * DM) + (size_t)row_u * DM + u.pn * BM);
.LBB0_395:
	s_andn2_b64 vcc, exec, s[4:5]
	s_cbranch_vccnz .LBB0_397
	s_cmpk_lg_u32 s72, 0x100
	s_cbranch_scc1 .Lmy_fn_orig
	v_readlane_b32 s2, v255, 0
	s_nop 3
	s_cmp_lg_u32 s17, 8
	s_cbranch_scc1 .Lmy_fn_c1
	s_cmp_lg_u32 s2, 1
	s_cbranch_scc1 .Lmy_fn_c1
	s_mov_b32 s92, 0
	s_movk_i32 s93, 8
	s_branch .Lmy_fn_go
.Lmy_fn_c1:
	s_cmp_lg_u32 s17, 4
	s_cbranch_scc1 .Lmy_fn_c2
	s_cmp_lg_u32 s2, 1
	s_cbranch_scc1 .Lmy_fn_c2
	s_mov_b32 s92, 1
	s_movk_i32 s93, 4
	s_mov_b32 s94, 135168
	s_movk_i32 s95, 4096
	s_movk_i32 s32, 8
	s_branch .Lmy_fn_go

; #define GAS __attribute__((address_space(1)))
; __device__ __forceinline__ void gemm_epilogue(LAS unsigned char* lds, const GD& gd, const f32x4 (&acc)[2][2][4][2], const Unit& u) {
;     ...
; #pragma unroll
;         for (int am = 0; am < 8 / MBR; ++am) {
;             const int ai = (am * MBR) >> 2, m0 = (am * MBR) & 3;
;             f32x4 xi[MBR][2][2];
; #pragma unroll
;             for (int mm = 0; mm < MBR; ++mm)
; #pragma unroll
;                 for (int bj = 0; bj < 2; ++bj)
; #pragma unroll
;                     for (int n = 0; n < 2; ++n) xi[mm][bj][n] = *(GAS const f32x4*)(xin + xoff + (ai * HALF + (m0 + mm) * 16) * DM + bj * HALF + n * 16);
;             asm volatile("" ::: "memory");
; #pragma unroll
;             for (int mm = 0; mm < MBR; ++mm)
; #pragma unroll
;                 for (int bj = 0; bj < 2; ++bj)
; #pragma unroll
;                     for (int n = 0; n < 2; ++n) *(GAS f32x4*)(xout + xoff + (ai * HALF + (m0 + mm) * 16) * DM + bj * HALF + n * 16) = xi[mm][bj][n] + gv[bj][n] * acc[ai][bj][m0 + mm][n];
;         }
.Lmy_fn_go:
	v_lshlrev_b64 v[148:149], 2, v[96:97]
	v_lshl_add_u64 v[146:147], s[44:45], 0, v[148:149]
	v_lshl_add_u64 v[150:151], s[46:47], 0, v[148:149]
	s_mov_b64 s[4:5], 0x0
	v_lshl_add_u64 v[192:193], v[146:147], 0, s[4:5]
	v_lshl_add_u64 v[196:197], v[150:151], 0, s[4:5]
	s_mov_b64 s[4:5], 0x10000
	v_lshl_add_u64 v[194:195], v[146:147], 0, s[4:5]
	v_lshl_add_u64 v[198:199], v[150:151], 0, s[4:5]
	global_load_dwordx4 v[152:155], v[192:193], off
	global_load_dwordx4 v[156:159], v[192:193], off offset:64
	global_load_dwordx4 v[160:163], v[192:193], off offset:512
	global_load_dwordx4 v[164:167], v[192:193], off offset:576
	global_load_dwordx4 v[168:171], v[194:195], off
	global_load_dwordx4 v[172:175], v[194:195], off offset:64
	global_load_dwordx4 v[176:179], v[194:195], off offset:512
	global_load_dwordx4 v[180:183], v[194:195], off offset:576
	s_waitcnt vmcnt(0)
	v_pk_fma_f32 v[126:127], v[126:127], v[142:143], v[152:153]
	v_pk_fma_f32 v[128:129], v[128:129], v[144:145], v[154:155]
	v_pk_fma_f32 v[4:5], v[4:5], v[138:139], v[156:157]
	v_pk_fma_f32 v[6:7], v[6:7], v[140:141], v[158:159]
	v_pk_fma_f32 v[48:49], v[48:49], v[134:135], v[160:161]
	v_pk_fma_f32 v[50:51], v[50:51], v[136:137], v[162:163]
	v_pk_fma_f32 v[12:13], v[12:13], v[130:131], v[164:165]
	v_pk_fma_f32 v[14:15], v[14:15], v[132:133], v[166:167]
	v_pk_fma_f32 v[122:123], v[122:123], v[142:143], v[168:169]
	v_pk_fma_f32 v[124:125], v[124:125], v[144:145], v[170:171]
	v_pk_fma_f32 v[118:119], v[118:119], v[138:139], v[172:173]
	v_pk_fma_f32 v[120:121], v[120:121], v[140:141], v[174:175]
	v_pk_fma_f32 v[102:103], v[102:103], v[134:135], v[176:177]
	v_pk_fma_f32 v[104:105], v[104:105], v[136:137], v[178:179]
	v_pk_fma_f32 v[98:99], v[98:99], v[130:131], v[180:181]
	v_pk_fma_f32 v[100:101], v[100:101], v[132:133], v[182:183]
	s_cmp_eq_u32 s92, 0
	s_cbranch_scc1 .Lmy_fn_ns0
	global_store_dwordx4 v[196:197], v[126:129], off
	global_store_dwordx4 v[196:197], v[4:7], off offset:64
	global_store_dwordx4 v[196:197], v[48:51], off offset:512
	global_store_dwordx4 v[196:197], v[12:15], off offset:576
	global_store_dwordx4 v[198:199], v[122:125], off
	global_store_dwordx4 v[198:199], v[118:121], off offset:64
	global_store_dwordx4 v[198:199], v[102:105], off offset:512
	global_store_dwordx4 v[198:199], v[98:101], off offset:576
.Lmy_fn_ns0:
	s_mov_b64 s[4:5], 0x20000
	v_lshl_add_u64 v[192:193], v[146:147], 0, s[4:5]
	v_lshl_add_u64 v[196:197], v[150:151], 0, s[4:5]
	s_mov_b64 s[4:5], 0x30000
	v_lshl_add_u64 v[194:195], v[146:147], 0, s[4:5]
	v_lshl_add_u64 v[198:199], v[150:151], 0, s[4:5]
	global_load_dwordx4 v[152:155], v[192:193], off
	global_load_dwordx4 v[156:159], v[192:193], off offset:64
	global_load_dwordx4 v[160:163], v[192:193], off offset:512
	global_load_dwordx4 v[164:167], v[192:193], off offset:576
	global_load_dwordx4 v[168:171], v[194:195], off
	global_load_dwordx4 v[172:175], v[194:195], off offset:64
	global_load_dwordx4 v[176:179], v[194:195], off offset:512
	global_load_dwordx4 v[180:183], v[194:195], off offset:576
	s_waitcnt vmcnt(0)
	v_pk_fma_f32 v[114:115], v[114:115], v[142:143], v[152:153]
	v_pk_fma_f32 v[116:117], v[116:117], v[144:145], v[154:155]
	v_pk_fma_f32 v[110:111], v[110:111], v[138:139], v[156:157]
	v_pk_fma_f32 v[112:113], v[112:113], v[140:141], v[158:159]
	v_pk_fma_f32 v[92:93], v[92:93], v[134:135], v[160:161]
	v_pk_fma_f32 v[94:95], v[94:95], v[136:137], v[162:163]
	v_pk_fma_f32 v[88:89], v[88:89], v[130:131], v[164:165]
	v_pk_fma_f32 v[90:91], v[90:91], v[132:133], v[166:167]
	v_pk_fma_f32 v[106:107], v[106:107], v[142:143], v[168:169]
	v_pk_fma_f32 v[108:109], v[108:109], v[144:145], v[170:171]
	v_pk_fma_f32 v[8:9], v[8:9], v[138:139], v[172:173]
	v_pk_fma_f32 v[10:11], v[10:11], v[140:141], v[174:175]
	v_pk_fma_f32 v[44:45], v[44:45], v[134:135], v[176:177]
	v_pk_fma_f32 v[46:47], v[46:47], v[136:137], v[178:179]
	v_pk_fma_f32 v[16:17], v[16:17], v[130:131], v[180:181]
	v_pk_fma_f32 v[18:19], v[18:19], v[132:133], v[182:183]
	s_cmp_eq_u32 s92, 0
	s_cbranch_scc1 .Lmy_fn_ns1
	global_store_dwordx4 v[196:197], v[114:117], off
	global_store_dwordx4 v[196:197], v[110:113], off offset:64
	global_store_dwordx4 v[196:197], v[92:95], off offset:512
	global_store_dwordx4 v[196:197], v[88:91], off offset:576
	global_store_dwordx4 v[198:199], v[106:109], off
	global_store_dwordx4 v[198:199], v[8:11], off offset:64
	global_store_dwordx4 v[198:199], v[44:47], off offset:512
	global_store_dwordx4 v[198:199], v[16:19], off offset:576
.Lmy_fn_ns1:
	s_mov_b64 s[4:5], 0x80000
	v_lshl_add_u64 v[192:193], v[146:147], 0, s[4:5]
	v_lshl_add_u64 v[196:197], v[150:151], 0, s[4:5]
	s_mov_b64 s[4:5], 0x90000
	v_lshl_add_u64 v[194:195], v[146:147], 0, s[4:5]
	v_lshl_add_u64 v[198:199], v[150:151], 0, s[4:5]
	global_load_dwordx4 v[152:155], v[192:193], off
	global_load_dwordx4 v[156:159], v[192:193], off offset:64
	global_load_dwordx4 v[160:163], v[192:193], off offset:512
	global_load_dwordx4 v[164:167], v[192:193], off offset:576
	global_load_dwordx4 v[168:171], v[194:195], off
	global_load_dwordx4 v[172:175], v[194:195], off offset:64
	global_load_dwordx4 v[176:179], v[194:195], off offset:512
	global_load_dwordx4 v[180:183], v[194:195], off offset:576
	s_waitcnt vmcnt(0)
	v_pk_fma_f32 v[84:85], v[84:85], v[142:143], v[152:153]
	v_pk_fma_f32 v[86:87], v[86:87], v[144:145], v[154:155]
	v_pk_fma_f32 v[20:21], v[20:21], v[138:139], v[156:157]
	v_pk_fma_f32 v[22:23], v[22:23], v[140:141], v[158:159]
	v_pk_fma_f32 v[40:41], v[40:41], v[134:135], v[160:161]
	v_pk_fma_f32 v[42:43], v[42:43], v[136:137], v[162:163]
	v_pk_fma_f32 v[28:29], v[28:29], v[130:131], v[164:165]
	v_pk_fma_f32 v[30:31], v[30:31], v[132:133], v[166:167]
	v_pk_fma_f32 v[80:81], v[80:81], v[142:143], v[168:169]
	v_pk_fma_f32 v[82:83], v[82:83], v[144:145], v[170:171]
	v_pk_fma_f32 v[76:77], v[76:77], v[138:139], v[172:173]
	v_pk_fma_f32 v[78:79], v[78:79], v[140:141], v[174:175]
	v_pk_fma_f32 v[60:61], v[60:61], v[134:135], v[176:177]
	v_pk_fma_f32 v[62:63], v[62:63], v[136:137], v[178:179]
	v_pk_fma_f32 v[56:57], v[56:57], v[130:131], v[180:181]
	v_pk_fma_f32 v[58:59], v[58:59], v[132:133], v[182:183]
	s_cmp_eq_u32 s92, 0
	s_cbranch_scc1 .Lmy_fn_ns2
	global_store_dwordx4 v[196:197], v[84:87], off
	global_store_dwordx4 v[196:197], v[20:23], off offset:64
	global_store_dwordx4 v[196:197], v[40:43], off offset:512
	global_store_dwordx4 v[196:197], v[28:31], off offset:576
	global_store_dwordx4 v[198:199], v[80:83], off
	global_store_dwordx4 v[198:199], v[76:79], off offset:64
	global_store_dwordx4 v[198:199], v[60:63], off offset:512
	global_store_dwordx4 v[198:199], v[56:59], off offset:576
; #define GAS __attribute__((address_space(1)))
; __device__ __forceinline__ void gemm_epilogue(LAS unsigned char* lds, const GD& gd, const f32x4 (&acc)[2][2][4][2], const Unit& u) {
;     ...
; #pragma unroll
;         for (int am = 0; am < 8 / MBR; ++am) {
;             const int ai = (am * MBR) >> 2, m0 = (am * MBR) & 3;
;             f32x4 xi[MBR][2][2];
; #pragma unroll
;             for (int mm = 0; mm < MBR; ++mm)
; #pragma unroll
;                 for (int bj = 0; bj < 2; ++bj)
; #pragma unroll
;                     for (int n = 0; n < 2; ++n) xi[mm][bj][n] = *(GAS const f32x4*)(xin + xoff + (ai * HALF + (m0 + mm) * 16) * DM + bj * HALF + n * 16);
;             asm volatile("" ::: "memory");
; #pragma unroll
;             for (int mm = 0; mm < MBR; ++mm)
; #pragma unroll
;                 for (int bj = 0; bj < 2; ++bj)
; #pragma unroll
;                     for (int n = 0; n < 2; ++n) *(GAS f32x4*)(xout + xoff + (ai * HALF + (m0 + mm) * 16) * DM + bj * HALF + n * 16) = xi[mm][bj][n] + gv[bj][n] * acc[ai][bj][m0 + mm][n];
;         }
.Lmy_fn_ns2:
	s_mov_b64 s[4:5], 0xa0000
	v_lshl_add_u64 v[192:193], v[146:147], 0, s[4:5]
	v_lshl_add_u64 v[196:197], v[150:151], 0, s[4:5]
	s_mov_b64 s[4:5], 0xb0000
	v_lshl_add_u64 v[194:195], v[146:147], 0, s[4:5]
	v_lshl_add_u64 v[198:199], v[150:151], 0, s[4:5]
	global_load_dwordx4 v[152:155], v[192:193], off
	global_load_dwordx4 v[156:159], v[192:193], off offset:64
	global_load_dwordx4 v[160:163], v[192:193], off offset:512
	global_load_dwordx4 v[164:167], v[192:193], off offset:576
	global_load_dwordx4 v[168:171], v[194:195], off
	global_load_dwordx4 v[172:175], v[194:195], off offset:64
	global_load_dwordx4 v[176:179], v[194:195], off offset:512
	global_load_dwordx4 v[180:183], v[194:195], off offset:576
	s_waitcnt vmcnt(0)
	v_pk_fma_f32 v[72:73], v[72:73], v[142:143], v[152:153]
	v_pk_fma_f32 v[74:75], v[74:75], v[144:145], v[154:155]
	v_pk_fma_f32 v[68:69], v[68:69], v[138:139], v[156:157]
	v_pk_fma_f32 v[70:71], v[70:71], v[140:141], v[158:159]
	v_pk_fma_f32 v[52:53], v[52:53], v[134:135], v[160:161]
	v_pk_fma_f32 v[54:55], v[54:55], v[136:137], v[162:163]
	v_pk_fma_f32 v[0:1], v[0:1], v[130:131], v[164:165]
	v_pk_fma_f32 v[2:3], v[2:3], v[132:133], v[166:167]
	v_pk_fma_f32 v[64:65], v[64:65], v[142:143], v[168:169]
	v_pk_fma_f32 v[66:67], v[66:67], v[144:145], v[170:171]
	v_pk_fma_f32 v[24:25], v[24:25], v[138:139], v[172:173]
	v_pk_fma_f32 v[26:27], v[26:27], v[140:141], v[174:175]
	v_pk_fma_f32 v[36:37], v[36:37], v[134:135], v[176:177]
	v_pk_fma_f32 v[38:39], v[38:39], v[136:137], v[178:179]
	v_pk_fma_f32 v[32:33], v[32:33], v[130:131], v[180:181]
	v_pk_fma_f32 v[34:35], v[34:35], v[132:133], v[182:183]
	s_cmp_eq_u32 s92, 0
	s_cbranch_scc1 .Lmy_fn_ns3
	global_store_dwordx4 v[196:197], v[72:75], off
	global_store_dwordx4 v[196:197], v[68:71], off offset:64
	global_store_dwordx4 v[196:197], v[52:55], off offset:512
	global_store_dwordx4 v[196:197], v[0:3], off offset:576
	global_store_dwordx4 v[198:199], v[64:67], off
	global_store_dwordx4 v[198:199], v[24:27], off offset:64
	global_store_dwordx4 v[198:199], v[36:39], off offset:512
	global_store_dwordx4 v[198:199], v[32:35], off offset:576
; __device__ void phase_norm(const Params& p, int l, int which) {
;     ...
;         float s = 0.f;
; #pragma unroll
;         for (int j = 0; j < 4; ++j) s += (v[j].x * v[j].x + v[j].y * v[j].y) + (v[j].z * v[j].z + v[j].w * v[j].w);
;         const float rstd = rsqrtf(wave_sum(s) * (1.f / 1024.f) + 1e-6f);
.Lmy_fn_ns3:
	v_pk_mul_f32 v[192:193], v[126:127], v[126:127]
	v_pk_fma_f32 v[192:193], v[128:129], v[128:129], v[192:193]
	v_pk_fma_f32 v[192:193], v[4:5], v[4:5], v[192:193]
	v_pk_fma_f32 v[192:193], v[6:7], v[6:7], v[192:193]
	v_pk_fma_f32 v[192:193], v[48:49], v[48:49], v[192:193]
	v_pk_fma_f32 v[192:193], v[50:51], v[50:51], v[192:193]
	v_pk_fma_f32 v[192:193], v[12:13], v[12:13], v[192:193]
	v_pk_fma_f32 v[192:193], v[14:15], v[14:15], v[192:193]
	v_add_f32_e32 v184, v192, v193
	v_pk_mul_f32 v[192:193], v[122:123], v[122:123]
	v_pk_fma_f32 v[192:193], v[124:125], v[124:125], v[192:193]
	v_pk_fma_f32 v[192:193], v[118:119], v[118:119], v[192:193]
	v_pk_fma_f32 v[192:193], v[120:121], v[120:121], v[192:193]
	v_pk_fma_f32 v[192:193], v[102:103], v[102:103], v[192:193]
	v_pk_fma_f32 v[192:193], v[104:105], v[104:105], v[192:193]
	v_pk_fma_f32 v[192:193], v[98:99], v[98:99], v[192:193]
	v_pk_fma_f32 v[192:193], v[100:101], v[100:101], v[192:193]
	v_add_f32_e32 v185, v192, v193
	v_pk_mul_f32 v[192:193], v[114:115], v[114:115]
	v_pk_fma_f32 v[192:193], v[116:117], v[116:117], v[192:193]
	v_pk_fma_f32 v[192:193], v[110:111], v[110:111], v[192:193]
	v_pk_fma_f32 v[192:193], v[112:113], v[112:113], v[192:193]
	v_pk_fma_f32 v[192:193], v[92:93], v[92:93], v[192:193]
	v_pk_fma_f32 v[192:193], v[94:95], v[94:95], v[192:193]
	v_pk_fma_f32 v[192:193], v[88:89], v[88:89], v[192:193]
	v_pk_fma_f32 v[192:193], v[90:91], v[90:91], v[192:193]
	v_add_f32_e32 v186, v192, v193
	v_pk_mul_f32 v[192:193], v[106:107], v[106:107]
	v_pk_fma_f32 v[192:193], v[108:109], v[108:109], v[192:193]
	v_pk_fma_f32 v[192:193], v[8:9], v[8:9], v[192:193]
	v_pk_fma_f32 v[192:193], v[10:11], v[10:11], v[192:193]
	v_pk_fma_f32 v[192:193], v[44:45], v[44:45], v[192:193]
	v_pk_fma_f32 v[192:193], v[46:47], v[46:47], v[192:193]
	v_pk_fma_f32 v[192:193], v[16:17], v[16:17], v[192:193]
	v_pk_fma_f32 v[192:193], v[18:19], v[18:19], v[192:193]
	v_add_f32_e32 v187, v192, v193
	v_pk_mul_f32 v[192:193], v[84:85], v[84:85]
	v_pk_fma_f32 v[192:193], v[86:87], v[86:87], v[192:193]
	v_pk_fma_f32 v[192:193], v[20:21], v[20:21], v[192:193]
	v_pk_fma_f32 v[192:193], v[22:23], v[22:23], v[192:193]
	v_pk_fma_f32 v[192:193], v[40:41], v[40:41], v[192:193]
	v_pk_fma_f32 v[192:193], v[42:43], v[42:43], v[192:193]
	v_pk_fma_f32 v[192:193], v[28:29], v[28:29], v[192:193]
	v_pk_fma_f32 v[192:193], v[30:31], v[30:31], v[192:193]
	v_add_f32_e32 v188, v192, v193
	v_pk_mul_f32 v[192:193], v[80:81], v[80:81]
	v_pk_fma_f32 v[192:193], v[82:83], v[82:83], v[192:193]
	v_pk_fma_f32 v[192:193], v[76:77], v[76:77], v[192:193]
	v_pk_fma_f32 v[192:193], v[78:79], v[78:79], v[192:193]
	v_pk_fma_f32 v[192:193], v[60:61], v[60:61], v[192:193]
	v_pk_fma_f32 v[192:193], v[62:63], v[62:63], v[192:193]
	v_pk_fma_f32 v[192:193], v[56:57], v[56:57], v[192:193]
	v_pk_fma_f32 v[192:193], v[58:59], v[58:59], v[192:193]
	v_add_f32_e32 v189, v192, v193
	v_pk_mul_f32 v[192:193], v[72:73], v[72:73]
	v_pk_fma_f32 v[192:193], v[74:75], v[74:75], v[192:193]
	v_pk_fma_f32 v[192:193], v[68:69], v[68:69], v[192:193]
	v_pk_fma_f32 v[192:193], v[70:71], v[70:71], v[192:193]
	v_pk_fma_f32 v[192:193], v[52:53], v[52:53], v[192:193]
	v_pk_fma_f32 v[192:193], v[54:55], v[54:55], v[192:193]
	v_pk_fma_f32 v[192:193], v[0:1], v[0:1], v[192:193]
	v_pk_fma_f32 v[192:193], v[2:3], v[2:3], v[192:193]
	v_add_f32_e32 v190, v192, v193
	v_pk_mul_f32 v[192:193], v[64:65], v[64:65]
	v_pk_fma_f32 v[192:193], v[66:67], v[66:67], v[192:193]
	v_pk_fma_f32 v[192:193], v[24:25], v[24:25], v[192:193]
	v_pk_fma_f32 v[192:193], v[26:27], v[26:27], v[192:193]
	v_pk_fma_f32 v[192:193], v[36:37], v[36:37], v[192:193]
	v_pk_fma_f32 v[192:193], v[38:39], v[38:39], v[192:193]
	v_pk_fma_f32 v[192:193], v[32:33], v[32:33], v[192:193]
	v_pk_fma_f32 v[192:193], v[34:35], v[34:35], v[192:193]
	v_add_f32_e32 v191, v192, v193
	s_cmp_lg_u32 s98, 0
	s_cbranch_scc1 .Lmy_fn_e0
	s_barrier
.Lmy_fn_e0:
	v_lshl_or_b32 v198, s98, 6, v252
	v_lshlrev_b32_e32 v194, 6, v198
	v_lshl_add_u32 v194, v251, 4, v194
	s_lshl_b32 s2, s15, 2
	s_add_i32 s2, s2, 0x20000
	v_add_u32_e32 v194, s2, v194
	ds_write_b32 v194, v184
	ds_write_b32 v194, v185 offset:1024
	ds_write_b32 v194, v186 offset:2048
	ds_write_b32 v194, v187 offset:3072
	ds_write_b32 v194, v188 offset:8192
	ds_write_b32 v194, v189 offset:9216
	ds_write_b32 v194, v190 offset:10240
	ds_write_b32 v194, v191 offset:11264
	s_waitcnt lgkmcnt(0)
	s_barrier
	s_cmp_lg_u32 s98, 0
	s_cbranch_scc1 .Lmy_fn_b1
	v_mov_b32_e32 v195, 0x240a8
	ds_read_b64 v[196:197], v195
	v_lshlrev_b32_e32 v194, 6, v210
	v_add_u32_e32 v194, 0x20000, v194
	ds_read_b128 v[152:155], v194
	ds_read_b128 v[156:159], v194 offset:16
	ds_read_b128 v[160:163], v194 offset:32
	ds_read_b128 v[164:167], v194 offset:48
	s_waitcnt lgkmcnt(0)
	v_readfirstlane_b32 s48, v196
	v_readfirstlane_b32 s49, v197
	v_add_f32_e32 v192, v152, v153
	v_add_f32_e32 v192, v192, v154
	v_add_f32_e32 v192, v192, v155
	v_add_f32_e32 v192, v192, v156
	v_add_f32_e32 v192, v192, v157
	v_add_f32_e32 v192, v192, v158
	v_add_f32_e32 v192, v192, v159
	v_add_f32_e32 v192, v192, v160
	v_add_f32_e32 v192, v192, v161
	v_add_f32_e32 v192, v192, v162
	v_add_f32_e32 v192, v192, v163
	v_add_f32_e32 v192, v192, v164
	v_add_f32_e32 v192, v192, v165
	v_add_f32_e32 v192, v192, v166
	v_add_f32_e32 v192, v192, v167
	s_add_u32 s50, s48, 0x100100
	s_addc_u32 s51, s49, 0
	s_cmp_lt_u32 s33, 64
	s_cbranch_scc1 .Lmy_fn_lat
	s_sub_u32 s50, s50, 0x1d0
	s_subb_u32 s51, s51, 0
.Lmy_fn_lat:
	s_lshl_b32 s2, s33, 2
	s_add_u32 s50, s50, s2
	s_addc_u32 s51, s51, 0
	s_add_u32 s48, s48, 0xf300000
	s_addc_u32 s49, s49, 0
	s_lshl_b32 s2, s33, 12
	s_add_u32 s48, s48, s2
	s_addc_u32 s49, s49, 0
	s_lshl_b32 s2, s80, 10
	v_lshlrev_b32_e32 v195, 2, v210
	v_add_u32_e32 v199, s2, v195
	global_atomic_swap v200, v199, v192, s[48:49] sc0
	s_waitcnt vmcnt(0)

.Lmy_fn_spin:
	global_load_dword v199, v97, s[50:51] sc1
	s_waitcnt vmcnt(0)
	v_readfirstlane_b32 s4, v199
	s_nop 3
	s_cmp_ge_u32 s4, s93
	s_cbranch_scc1 .Lmy_fn_nof
	s_add_i32 s2, s2, 1
	s_cmp_lt_u32 s2, 0x4000
	s_cbranch_scc0 .Lmy_fn_nof
	s_sleep 1
	s_branch .Lmy_fn_spin

; __device__ __forceinline__ int otid() { int t = threadIdx.x; asm volatile("" : "+v"(t)); return t; }
; #define GAS __attribute__((address_space(1)))
; __device__ void phase_final(const Params& p) {
;     const int tid = otid(), lane = tid & 63, gw = blockIdx.x * 8 + (tid >> 6), nw = gridDim.x * 8;
;     GAS const f32x4* gf = (GAS const f32x4*)(unsigned long long)p.norm_final;
;     for (int row = gw; row < NL; row += nw) {
;         GAS f32x4* xr = (GAS f32x4*)(unsigned long long)(p.out + (size_t)row * DM);
;         f32x4 v[4], g4[4];
; #pragma unroll
;         for (int j = 0; j < 4; ++j) { v[j] = xr[lane + 64 * j]; g4[j] = gf[lane + 64 * j]; }
;         asm volatile("" ::: "memory");
;         float s = 0.f;
; #pragma unroll
;         for (int j = 0; j < 4; ++j) s += (v[j].x * v[j].x + v[j].y * v[j].y) + (v[j].z * v[j].z + v[j].w * v[j].w);
;         const float rstd = rsqrtf(wave_sum(s) * (1.f / 1024.f) + 1e-6f);
; #pragma unroll
;         for (int j = 0; j < 4; ++j) xr[lane + 64 * j] = v[j] * rstd * g4[j];
.Lmy_fn_b2:
	s_barrier
	v_lshl_or_b32 v198, s98, 6, v252
	v_lshlrev_b32_e32 v194, 2, v198
	v_add_u32_e32 v194, 0x20000, v194
	ds_read_b32 v184, v194
	ds_read_b32 v185, v194 offset:64
	ds_read_b32 v186, v194 offset:128
	ds_read_b32 v187, v194 offset:192
	ds_read_b32 v188, v194 offset:512
	ds_read_b32 v189, v194 offset:576
	ds_read_b32 v190, v194 offset:640
	ds_read_b32 v191, v194 offset:704
	v_lshlrev_b32_e32 v139, 2, v251
	v_lshl_or_b32 v139, s15, 5, v139
	v_lshlrev_b32_e32 v139, 2, v139
	s_cmp_eq_u32 s92, 0
	s_cbranch_scc0 .Lmy_fn_norm
	v_readlane_b32 s2, v254, 41
	s_nop 3
	v_mov_b32_e32 v130, s2
	ds_read_b64 v[132:133], v130
	s_waitcnt lgkmcnt(0)
	v_readfirstlane_b32 s4, v132
	v_readfirstlane_b32 s5, v133
	s_lshl_b32 s2, s80, 10
	s_add_u32 s4, s4, s2
	s_addc_u32 s5, s5, 0
	global_load_dwordx4 v[152:155], v139, s[4:5]
	global_load_dwordx4 v[156:159], v139, s[4:5] offset:64
	global_load_dwordx4 v[160:163], v139, s[4:5] offset:512
	global_load_dwordx4 v[164:167], v139, s[4:5] offset:576
	s_waitcnt vmcnt(0)
	s_mov_b64 s[4:5], 0x0
	v_lshl_add_u64 v[130:131], v[150:151], 0, s[4:5]
	v_mul_f32_e32 v126, v126, v184
	v_mul_f32_e32 v127, v127, v184
	v_mul_f32_e32 v128, v128, v184
	v_mul_f32_e32 v129, v129, v184
	v_pk_mul_f32 v[126:127], v[152:153], v[126:127]
	v_pk_mul_f32 v[128:129], v[154:155], v[128:129]
	global_store_dwordx4 v[130:131], v[126:129], off
	v_mul_f32_e32 v4, v4, v184
	v_mul_f32_e32 v5, v5, v184
	v_mul_f32_e32 v6, v6, v184
	v_mul_f32_e32 v7, v7, v184
	v_pk_mul_f32 v[4:5], v[156:157], v[4:5]
	v_pk_mul_f32 v[6:7], v[158:159], v[6:7]
	global_store_dwordx4 v[130:131], v[4:7], off offset:64
	v_mul_f32_e32 v48, v48, v184
	v_mul_f32_e32 v49, v49, v184
	v_mul_f32_e32 v50, v50, v184
	v_mul_f32_e32 v51, v51, v184
	v_pk_mul_f32 v[48:49], v[160:161], v[48:49]
	v_pk_mul_f32 v[50:51], v[162:163], v[50:51]
	global_store_dwordx4 v[130:131], v[48:51], off offset:512
	v_mul_f32_e32 v12, v12, v184
	v_mul_f32_e32 v13, v13, v184
	v_mul_f32_e32 v14, v14, v184
	v_mul_f32_e32 v15, v15, v184
	v_pk_mul_f32 v[12:13], v[164:165], v[12:13]
	v_pk_mul_f32 v[14:15], v[166:167], v[14:15]
	global_store_dwordx4 v[130:131], v[12:15], off offset:576
	s_mov_b64 s[4:5], 0x10000
	v_lshl_add_u64 v[130:131], v[150:151], 0, s[4:5]
	v_mul_f32_e32 v122, v122, v185
	v_mul_f32_e32 v123, v123, v185
	v_mul_f32_e32 v124, v124, v185
	v_mul_f32_e32 v125, v125, v185
	v_pk_mul_f32 v[122:123], v[152:153], v[122:123]
	v_pk_mul_f32 v[124:125], v[154:155], v[124:125]
	global_store_dwordx4 v[130:131], v[122:125], off
	v_mul_f32_e32 v118, v118, v185
	v_mul_f32_e32 v119, v119, v185
	v_mul_f32_e32 v120, v120, v185
	v_mul_f32_e32 v121, v121, v185
	v_pk_mul_f32 v[118:119], v[156:157], v[118:119]
	v_pk_mul_f32 v[120:121], v[158:159], v[120:121]
	global_store_dwordx4 v[130:131], v[118:121], off offset:64
	v_mul_f32_e32 v102, v102, v185
	v_mul_f32_e32 v103, v103, v185
	v_mul_f32_e32 v104, v104, v185
	v_mul_f32_e32 v105, v105, v185
	v_pk_mul_f32 v[102:103], v[160:161], v[102:103]
	v_pk_mul_f32 v[104:105], v[162:163], v[104:105]
	global_store_dwordx4 v[130:131], v[102:105], off offset:512
	v_mul_f32_e32 v98, v98, v185
	v_mul_f32_e32 v99, v99, v185
	v_mul_f32_e32 v100, v100, v185
	v_mul_f32_e32 v101, v101, v185
	v_pk_mul_f32 v[98:99], v[164:165], v[98:99]
	v_pk_mul_f32 v[100:101], v[166:167], v[100:101]
	global_store_dwordx4 v[130:131], v[98:101], off offset:576
	s_mov_b64 s[4:5], 0x20000
	v_lshl_add_u64 v[130:131], v[150:151], 0, s[4:5]
	v_mul_f32_e32 v114, v114, v186
	v_mul_f32_e32 v115, v115, v186
	v_mul_f32_e32 v116, v116, v186
	v_mul_f32_e32 v117, v117, v186
	v_pk_mul_f32 v[114:115], v[152:153], v[114:115]
	v_pk_mul_f32 v[116:117], v[154:155], v[116:117]
	global_store_dwordx4 v[130:131], v[114:117], off
	v_mul_f32_e32 v110, v110, v186
	v_mul_f32_e32 v111, v111, v186
	v_mul_f32_e32 v112, v112, v186
	v_mul_f32_e32 v113, v113, v186
	v_pk_mul_f32 v[110:111], v[156:157], v[110:111]
	v_pk_mul_f32 v[112:113], v[158:159], v[112:113]
	global_store_dwordx4 v[130:131], v[110:113], off offset:64
	v_mul_f32_e32 v92, v92, v186
	v_mul_f32_e32 v93, v93, v186
	v_mul_f32_e32 v94, v94, v186
	v_mul_f32_e32 v95, v95, v186
	v_pk_mul_f32 v[92:93], v[160:161], v[92:93]
	v_pk_mul_f32 v[94:95], v[162:163], v[94:95]
	global_store_dwordx4 v[130:131], v[92:95], off offset:512
	v_mul_f32_e32 v88, v88, v186
	v_mul_f32_e32 v89, v89, v186
	v_mul_f32_e32 v90, v90, v186
	v_mul_f32_e32 v91, v91, v186
	v_pk_mul_f32 v[88:89], v[164:165], v[88:89]
	v_pk_mul_f32 v[90:91], v[166:167], v[90:91]
	global_store_dwordx4 v[130:131], v[88:91], off offset:576
	s_mov_b64 s[4:5], 0x30000
	v_lshl_add_u64 v[130:131], v[150:151], 0, s[4:5]
	v_mul_f32_e32 v106, v106, v187
	v_mul_f32_e32 v107, v107, v187
	v_mul_f32_e32 v108, v108, v187
	v_mul_f32_e32 v109, v109, v187
	v_pk_mul_f32 v[106:107], v[152:153], v[106:107]
	v_pk_mul_f32 v[108:109], v[154:155], v[108:109]
	global_store_dwordx4 v[130:131], v[106:109], off
	v_mul_f32_e32 v8, v8, v187
	v_mul_f32_e32 v9, v9, v187
	v_mul_f32_e32 v10, v10, v187
	v_mul_f32_e32 v11, v11, v187
	v_pk_mul_f32 v[8:9], v[156:157], v[8:9]
	v_pk_mul_f32 v[10:11], v[158:159], v[10:11]
	global_store_dwordx4 v[130:131], v[8:11], off offset:64
	v_mul_f32_e32 v44, v44, v187
	v_mul_f32_e32 v45, v45, v187
	v_mul_f32_e32 v46, v46, v187
	v_mul_f32_e32 v47, v47, v187
	v_pk_mul_f32 v[44:45], v[160:161], v[44:45]
	v_pk_mul_f32 v[46:47], v[162:163], v[46:47]
	global_store_dwordx4 v[130:131], v[44:47], off offset:512
	v_mul_f32_e32 v16, v16, v187
	v_mul_f32_e32 v17, v17, v187
	v_mul_f32_e32 v18, v18, v187
	v_mul_f32_e32 v19, v19, v187
	v_pk_mul_f32 v[16:17], v[164:165], v[16:17]
	v_pk_mul_f32 v[18:19], v[166:167], v[18:19]
; __device__ void phase_final(const Params& p) {
;     ...
;         const float rstd = rsqrtf(wave_sum(s) * (1.f / 1024.f) + 1e-6f);
; #pragma unroll
;         for (int j = 0; j < 4; ++j) xr[lane + 64 * j] = v[j] * rstd * g4[j];
	global_store_dwordx4 v[130:131], v[16:19], off offset:576
	s_mov_b64 s[4:5], 0x80000
	v_lshl_add_u64 v[130:131], v[150:151], 0, s[4:5]
	v_mul_f32_e32 v84, v84, v188
	v_mul_f32_e32 v85, v85, v188
	v_mul_f32_e32 v86, v86, v188
	v_mul_f32_e32 v87, v87, v188
	v_pk_mul_f32 v[84:85], v[152:153], v[84:85]
	v_pk_mul_f32 v[86:87], v[154:155], v[86:87]
	global_store_dwordx4 v[130:131], v[84:87], off
	v_mul_f32_e32 v20, v20, v188
	v_mul_f32_e32 v21, v21, v188
	v_mul_f32_e32 v22, v22, v188
	v_mul_f32_e32 v23, v23, v188
	v_pk_mul_f32 v[20:21], v[156:157], v[20:21]
	v_pk_mul_f32 v[22:23], v[158:159], v[22:23]
	global_store_dwordx4 v[130:131], v[20:23], off offset:64
	v_mul_f32_e32 v40, v40, v188
	v_mul_f32_e32 v41, v41, v188
	v_mul_f32_e32 v42, v42, v188
	v_mul_f32_e32 v43, v43, v188
	v_pk_mul_f32 v[40:41], v[160:161], v[40:41]
	v_pk_mul_f32 v[42:43], v[162:163], v[42:43]
	global_store_dwordx4 v[130:131], v[40:43], off offset:512
	v_mul_f32_e32 v28, v28, v188
	v_mul_f32_e32 v29, v29, v188
	v_mul_f32_e32 v30, v30, v188
	v_mul_f32_e32 v31, v31, v188
	v_pk_mul_f32 v[28:29], v[164:165], v[28:29]
	v_pk_mul_f32 v[30:31], v[166:167], v[30:31]
	global_store_dwordx4 v[130:131], v[28:31], off offset:576
	s_mov_b64 s[4:5], 0x90000
	v_lshl_add_u64 v[130:131], v[150:151], 0, s[4:5]
	v_mul_f32_e32 v80, v80, v189
	v_mul_f32_e32 v81, v81, v189
	v_mul_f32_e32 v82, v82, v189
	v_mul_f32_e32 v83, v83, v189
	v_pk_mul_f32 v[80:81], v[152:153], v[80:81]
	v_pk_mul_f32 v[82:83], v[154:155], v[82:83]
	global_store_dwordx4 v[130:131], v[80:83], off
	v_mul_f32_e32 v76, v76, v189
	v_mul_f32_e32 v77, v77, v189
	v_mul_f32_e32 v78, v78, v189
	v_mul_f32_e32 v79, v79, v189
	v_pk_mul_f32 v[76:77], v[156:157], v[76:77]
	v_pk_mul_f32 v[78:79], v[158:159], v[78:79]
	global_store_dwordx4 v[130:131], v[76:79], off offset:64
	v_mul_f32_e32 v60, v60, v189
	v_mul_f32_e32 v61, v61, v189
	v_mul_f32_e32 v62, v62, v189
	v_mul_f32_e32 v63, v63, v189
	v_pk_mul_f32 v[60:61], v[160:161], v[60:61]
	v_pk_mul_f32 v[62:63], v[162:163], v[62:63]
	global_store_dwordx4 v[130:131], v[60:63], off offset:512
	v_mul_f32_e32 v56, v56, v189
	v_mul_f32_e32 v57, v57, v189
	v_mul_f32_e32 v58, v58, v189
	v_mul_f32_e32 v59, v59, v189
	v_pk_mul_f32 v[56:57], v[164:165], v[56:57]
	v_pk_mul_f32 v[58:59], v[166:167], v[58:59]
	global_store_dwordx4 v[130:131], v[56:59], off offset:576
	s_mov_b64 s[4:5], 0xa0000
	v_lshl_add_u64 v[130:131], v[150:151], 0, s[4:5]
	v_mul_f32_e32 v72, v72, v190
	v_mul_f32_e32 v73, v73, v190
	v_mul_f32_e32 v74, v74, v190
	v_mul_f32_e32 v75, v75, v190
	v_pk_mul_f32 v[72:73], v[152:153], v[72:73]
	v_pk_mul_f32 v[74:75], v[154:155], v[74:75]
	global_store_dwordx4 v[130:131], v[72:75], off
	v_mul_f32_e32 v68, v68, v190
	v_mul_f32_e32 v69, v69, v190
	v_mul_f32_e32 v70, v70, v190
	v_mul_f32_e32 v71, v71, v190
	v_pk_mul_f32 v[68:69], v[156:157], v[68:69]
	v_pk_mul_f32 v[70:71], v[158:159], v[70:71]
	global_store_dwordx4 v[130:131], v[68:71], off offset:64
	v_mul_f32_e32 v52, v52, v190
	v_mul_f32_e32 v53, v53, v190
	v_mul_f32_e32 v54, v54, v190
	v_mul_f32_e32 v55, v55, v190
	v_pk_mul_f32 v[52:53], v[160:161], v[52:53]
	v_pk_mul_f32 v[54:55], v[162:163], v[54:55]
	global_store_dwordx4 v[130:131], v[52:55], off offset:512
	v_mul_f32_e32 v0, v0, v190
	v_mul_f32_e32 v1, v1, v190
	v_mul_f32_e32 v2, v2, v190
	v_mul_f32_e32 v3, v3, v190
	v_pk_mul_f32 v[0:1], v[164:165], v[0:1]
	v_pk_mul_f32 v[2:3], v[166:167], v[2:3]
	global_store_dwordx4 v[130:131], v[0:3], off offset:576
	s_mov_b64 s[4:5], 0xb0000
	v_lshl_add_u64 v[130:131], v[150:151], 0, s[4:5]
	v_mul_f32_e32 v64, v64, v191
	v_mul_f32_e32 v65, v65, v191
	v_mul_f32_e32 v66, v66, v191
	v_mul_f32_e32 v67, v67, v191
	v_pk_mul_f32 v[64:65], v[152:153], v[64:65]
	v_pk_mul_f32 v[66:67], v[154:155], v[66:67]
	global_store_dwordx4 v[130:131], v[64:67], off
	v_mul_f32_e32 v24, v24, v191
	v_mul_f32_e32 v25, v25, v191
	v_mul_f32_e32 v26, v26, v191
	v_mul_f32_e32 v27, v27, v191
	v_pk_mul_f32 v[24:25], v[156:157], v[24:25]
	v_pk_mul_f32 v[26:27], v[158:159], v[26:27]
	global_store_dwordx4 v[130:131], v[24:27], off offset:64
	v_mul_f32_e32 v36, v36, v191
	v_mul_f32_e32 v37, v37, v191
	v_mul_f32_e32 v38, v38, v191
	v_mul_f32_e32 v39, v39, v191
	v_pk_mul_f32 v[36:37], v[160:161], v[36:37]
	v_pk_mul_f32 v[38:39], v[162:163], v[38:39]
	global_store_dwordx4 v[130:131], v[36:39], off offset:512
	v_mul_f32_e32 v32, v32, v191
	v_mul_f32_e32 v33, v33, v191
	v_mul_f32_e32 v34, v34, v191
	v_mul_f32_e32 v35, v35, v191
	v_pk_mul_f32 v[32:33], v[164:165], v[32:33]
	v_pk_mul_f32 v[34:35], v[166:167], v[34:35]
	global_store_dwordx4 v[130:131], v[32:35], off offset:576
	s_branch .Lmy_fn_done
; __device__ __forceinline__ unsigned pk2(float lo, float hi) { unsigned r; asm volatile("v_cvt_pk_bf16_f32 %0, %1, %2" : "=v"(r) : "v"(lo), "v"(hi)); return r; }
; #define GAS __attribute__((address_space(1)))
; __device__ void phase_norm(const Params& p, int l, int which) {
;     ...
;         GAS const f32x4* sh = (GAS const f32x4*)(mod + rb * 6144); GAS const f32x4* sc = (GAS const f32x4*)(mod + rb * 6144 + 1024);
;         f32x4 v[4], g4[4], s4[4], h4[4];
; #pragma unroll
;         for (int j = 0; j < 4; ++j) { v[j] = xr[lane + 64 * j]; g4[j] = gn[lane + 64 * j]; s4[j] = sc[lane + 64 * j]; h4[j] = sh[lane + 64 * j]; }
;         asm volatile("" ::: "memory");
;         if (l == 1 && which == 0 && row >= NL) {
;             GAS const f32x4* pp = (GAS const f32x4*)(unsigned long long)((const float*)(p.ws + OFF_PART) + (size_t)(row - NL) * DM);
; #pragma unroll 1
;             for (int ks = 0; ks < SK_S; ++ks) {
;                 f32x4 t[4];
; #pragma unroll
;                 for (int j = 0; j < 4; ++j) t[j] = pp[(size_t)ks * (1024 * DM / 4) + lane + 64 * j];
;                 asm volatile("" ::: "memory");
; #pragma unroll
;                 for (int j = 0; j < 4; ++j) v[j] += t[j];
;             }
;         }
;         float s = 0.f;
; #pragma unroll
;         for (int j = 0; j < 4; ++j) s += (v[j].x * v[j].x + v[j].y * v[j].y) + (v[j].z * v[j].z + v[j].w * v[j].w);
;         const float rstd = rsqrtf(wave_sum(s) * (1.f / 1024.f) + 1e-6f);
; #pragma unroll
;         for (int j = 0; j < 4; ++j) {
;             const f32x4 y = v[j] * rstd * g4[j] * (s4[j] + 1.f) + h4[j];
;             u32x2 o; o.x = pk2(y.x, y.y); o.y = pk2(y.z, y.w);
;             ((GAS u32x2*)(H + (size_t)row * DM))[lane + 64 * j] = o;
.Lmy_fn_norm:
	v_mov_b32_e32 v130, 0x240a8
	ds_read_b64 v[132:133], v130
	v_readlane_b32 s2, v254, 40
	s_nop 3
	v_mov_b32_e32 v130, s2
	v_add_u32_e32 v130, s32, v130
	ds_read_b64 v[134:135], v130
	s_waitcnt lgkmcnt(0)
	v_readfirstlane_b32 s48, v132
	v_readfirstlane_b32 s49, v133
	v_readfirstlane_b32 s4, v134
	v_readfirstlane_b32 s5, v135
	s_lshl_b32 s2, s80, 10
	s_add_u32 s2, s2, s95
	s_add_u32 s4, s4, s2
	s_addc_u32 s5, s5, 0
	global_load_dwordx4 v[152:155], v139, s[4:5]
	global_load_dwordx4 v[156:159], v139, s[4:5] offset:64
	global_load_dwordx4 v[160:163], v139, s[4:5] offset:512
	global_load_dwordx4 v[164:167], v139, s[4:5] offset:576
	s_min_i32 s2, s88, 0x4000
	s_ashr_i32 s2, s2, 12
	s_mul_i32 s2, s2, 0x6000
	s_add_u32 s2, s2, s94
	s_lshl_b32 s4, s80, 10
	s_add_u32 s2, s2, s4
	s_add_u32 s4, s48, s2
	s_addc_u32 s5, s49, 0
	global_load_dwordx4 v[192:195], v139, s[4:5]
	global_load_dwordx4 v[196:199], v139, s[4:5] offset:64
	global_load_dwordx4 v[200:203], v139, s[4:5] offset:512
	global_load_dwordx4 v[204:207], v139, s[4:5] offset:576
	s_add_u32 s4, s4, 0x1000
	s_addc_u32 s5, s5, 0
	global_load_dwordx4 v[168:171], v139, s[4:5]
	global_load_dwordx4 v[172:175], v139, s[4:5] offset:64
	global_load_dwordx4 v[176:179], v139, s[4:5] offset:512
	global_load_dwordx4 v[180:183], v139, s[4:5] offset:576
	s_lshl_b32 s2, s88, 11
	s_lshl_b32 s4, s80, 9
	s_add_u32 s2, s2, s4
	s_add_u32 s2, s2, 0x4100000
	s_add_u32 s4, s48, s2
	s_addc_u32 s5, s49, 0
	v_lshl_or_b32 v136, s98, 6, v252
	v_lshlrev_b32_e32 v140, 11, v136
	v_lshrrev_b32_e32 v136, 1, v139
	v_add_u32_e32 v140, v140, v136
	v_mov_b32_e32 v141, 0
	v_lshl_add_u64 v[144:145], s[4:5], 0, v[140:141]
	s_waitcnt vmcnt(0)
	v_pk_add_f32 v[168:169], v[168:169], 1.0 op_sel_hi:[1,0]
	v_pk_add_f32 v[170:171], v[170:171], 1.0 op_sel_hi:[1,0]
	v_pk_add_f32 v[172:173], v[172:173], 1.0 op_sel_hi:[1,0]
	v_pk_add_f32 v[174:175], v[174:175], 1.0 op_sel_hi:[1,0]
	v_pk_add_f32 v[176:177], v[176:177], 1.0 op_sel_hi:[1,0]
	v_pk_add_f32 v[178:179], v[178:179], 1.0 op_sel_hi:[1,0]
	v_pk_add_f32 v[180:181], v[180:181], 1.0 op_sel_hi:[1,0]
	v_pk_add_f32 v[182:183], v[182:183], 1.0 op_sel_hi:[1,0]
	s_mov_b64 s[4:5], 0x0
	v_lshl_add_u64 v[142:143], v[144:145], 0, s[4:5]
	v_mul_f32_e32 v126, v126, v184
	v_mul_f32_e32 v127, v127, v184
	v_mul_f32_e32 v128, v128, v184
	v_mul_f32_e32 v129, v129, v184
	v_pk_mul_f32 v[126:127], v[152:153], v[126:127]
	v_pk_mul_f32 v[128:129], v[154:155], v[128:129]
	v_pk_fma_f32 v[126:127], v[168:169], v[126:127], v[192:193]
	v_pk_fma_f32 v[128:129], v[170:171], v[128:129], v[194:195]
	v_cvt_pk_bf16_f32 v126, v126, v127
	v_cvt_pk_bf16_f32 v127, v128, v129
	global_store_dwordx2 v[142:143], v[126:127], off
	v_mul_f32_e32 v4, v4, v184
	v_mul_f32_e32 v5, v5, v184
	v_mul_f32_e32 v6, v6, v184
	v_mul_f32_e32 v7, v7, v184
	v_pk_mul_f32 v[4:5], v[156:157], v[4:5]
	v_pk_mul_f32 v[6:7], v[158:159], v[6:7]
	v_pk_fma_f32 v[4:5], v[172:173], v[4:5], v[196:197]
	v_pk_fma_f32 v[6:7], v[174:175], v[6:7], v[198:199]
	v_cvt_pk_bf16_f32 v4, v4, v5
	v_cvt_pk_bf16_f32 v5, v6, v7
	global_store_dwordx2 v[142:143], v[4:5], off offset:32
	v_mul_f32_e32 v48, v48, v184
	v_mul_f32_e32 v49, v49, v184
	v_mul_f32_e32 v50, v50, v184
	v_mul_f32_e32 v51, v51, v184
	v_pk_mul_f32 v[48:49], v[160:161], v[48:49]
	v_pk_mul_f32 v[50:51], v[162:163], v[50:51]
	v_pk_fma_f32 v[48:49], v[176:177], v[48:49], v[200:201]
	v_pk_fma_f32 v[50:51], v[178:179], v[50:51], v[202:203]
	v_cvt_pk_bf16_f32 v48, v48, v49
	v_cvt_pk_bf16_f32 v49, v50, v51
	global_store_dwordx2 v[142:143], v[48:49], off offset:256
	v_mul_f32_e32 v12, v12, v184
	v_mul_f32_e32 v13, v13, v184
	v_mul_f32_e32 v14, v14, v184
	v_mul_f32_e32 v15, v15, v184
	v_pk_mul_f32 v[12:13], v[164:165], v[12:13]
	v_pk_mul_f32 v[14:15], v[166:167], v[14:15]
	v_pk_fma_f32 v[12:13], v[180:181], v[12:13], v[204:205]
	v_pk_fma_f32 v[14:15], v[182:183], v[14:15], v[206:207]
	v_cvt_pk_bf16_f32 v12, v12, v13
	v_cvt_pk_bf16_f32 v13, v14, v15
	global_store_dwordx2 v[142:143], v[12:13], off offset:288
	s_mov_b64 s[4:5], 0x8000
	v_lshl_add_u64 v[142:143], v[144:145], 0, s[4:5]
	v_mul_f32_e32 v122, v122, v185
	v_mul_f32_e32 v123, v123, v185
	v_mul_f32_e32 v124, v124, v185
	v_mul_f32_e32 v125, v125, v185
	v_pk_mul_f32 v[122:123], v[152:153], v[122:123]
	v_pk_mul_f32 v[124:125], v[154:155], v[124:125]
	v_pk_fma_f32 v[122:123], v[168:169], v[122:123], v[192:193]
	v_pk_fma_f32 v[124:125], v[170:171], v[124:125], v[194:195]
	v_cvt_pk_bf16_f32 v122, v122, v123
	v_cvt_pk_bf16_f32 v123, v124, v125
	global_store_dwordx2 v[142:143], v[122:123], off
	v_mul_f32_e32 v118, v118, v185
	v_mul_f32_e32 v119, v119, v185
	v_mul_f32_e32 v120, v120, v185
	v_mul_f32_e32 v121, v121, v185
	v_pk_mul_f32 v[118:119], v[156:157], v[118:119]
	v_pk_mul_f32 v[120:121], v[158:159], v[120:121]
	v_pk_fma_f32 v[118:119], v[172:173], v[118:119], v[196:197]
	v_pk_fma_f32 v[120:121], v[174:175], v[120:121], v[198:199]
	v_cvt_pk_bf16_f32 v118, v118, v119
	v_cvt_pk_bf16_f32 v119, v120, v121
	global_store_dwordx2 v[142:143], v[118:119], off offset:32
	v_mul_f32_e32 v102, v102, v185
	v_mul_f32_e32 v103, v103, v185
	v_mul_f32_e32 v104, v104, v185
	v_mul_f32_e32 v105, v105, v185
	v_pk_mul_f32 v[102:103], v[160:161], v[102:103]
	v_pk_mul_f32 v[104:105], v[162:163], v[104:105]
	v_pk_fma_f32 v[102:103], v[176:177], v[102:103], v[200:201]
	v_pk_fma_f32 v[104:105], v[178:179], v[104:105], v[202:203]
	v_cvt_pk_bf16_f32 v102, v102, v103
	v_cvt_pk_bf16_f32 v103, v104, v105
	global_store_dwordx2 v[142:143], v[102:103], off offset:256
	v_mul_f32_e32 v98, v98, v185
	v_mul_f32_e32 v99, v99, v185
	v_mul_f32_e32 v100, v100, v185
	v_mul_f32_e32 v101, v101, v185
; __device__ __forceinline__ unsigned pk2(float lo, float hi) { unsigned r; asm volatile("v_cvt_pk_bf16_f32 %0, %1, %2" : "=v"(r) : "v"(lo), "v"(hi)); return r; }
; #define GAS __attribute__((address_space(1)))
; __device__ void phase_norm(const Params& p, int l, int which) {
;     ...
; #pragma unroll
;         for (int j = 0; j < 4; ++j) {
;             const f32x4 y = v[j] * rstd * g4[j] * (s4[j] + 1.f) + h4[j];
;             u32x2 o; o.x = pk2(y.x, y.y); o.y = pk2(y.z, y.w);
;             ((GAS u32x2*)(H + (size_t)row * DM))[lane + 64 * j] = o;
;         }
	v_pk_mul_f32 v[98:99], v[164:165], v[98:99]
	v_pk_mul_f32 v[100:101], v[166:167], v[100:101]
	v_pk_fma_f32 v[98:99], v[180:181], v[98:99], v[204:205]
	v_pk_fma_f32 v[100:101], v[182:183], v[100:101], v[206:207]
	v_cvt_pk_bf16_f32 v98, v98, v99
	v_cvt_pk_bf16_f32 v99, v100, v101
	global_store_dwordx2 v[142:143], v[98:99], off offset:288
	s_mov_b64 s[4:5], 0x10000
	v_lshl_add_u64 v[142:143], v[144:145], 0, s[4:5]
	v_mul_f32_e32 v114, v114, v186
	v_mul_f32_e32 v115, v115, v186
	v_mul_f32_e32 v116, v116, v186
	v_mul_f32_e32 v117, v117, v186
	v_pk_mul_f32 v[114:115], v[152:153], v[114:115]
	v_pk_mul_f32 v[116:117], v[154:155], v[116:117]
	v_pk_fma_f32 v[114:115], v[168:169], v[114:115], v[192:193]
	v_pk_fma_f32 v[116:117], v[170:171], v[116:117], v[194:195]
	v_cvt_pk_bf16_f32 v114, v114, v115
	v_cvt_pk_bf16_f32 v115, v116, v117
	global_store_dwordx2 v[142:143], v[114:115], off
	v_mul_f32_e32 v110, v110, v186
	v_mul_f32_e32 v111, v111, v186
	v_mul_f32_e32 v112, v112, v186
	v_mul_f32_e32 v113, v113, v186
	v_pk_mul_f32 v[110:111], v[156:157], v[110:111]
	v_pk_mul_f32 v[112:113], v[158:159], v[112:113]
	v_pk_fma_f32 v[110:111], v[172:173], v[110:111], v[196:197]
	v_pk_fma_f32 v[112:113], v[174:175], v[112:113], v[198:199]
	v_cvt_pk_bf16_f32 v110, v110, v111
	v_cvt_pk_bf16_f32 v111, v112, v113
	global_store_dwordx2 v[142:143], v[110:111], off offset:32
	v_mul_f32_e32 v92, v92, v186
	v_mul_f32_e32 v93, v93, v186
	v_mul_f32_e32 v94, v94, v186
	v_mul_f32_e32 v95, v95, v186
	v_pk_mul_f32 v[92:93], v[160:161], v[92:93]
	v_pk_mul_f32 v[94:95], v[162:163], v[94:95]
	v_pk_fma_f32 v[92:93], v[176:177], v[92:93], v[200:201]
	v_pk_fma_f32 v[94:95], v[178:179], v[94:95], v[202:203]
	v_cvt_pk_bf16_f32 v92, v92, v93
	v_cvt_pk_bf16_f32 v93, v94, v95
	global_store_dwordx2 v[142:143], v[92:93], off offset:256
	v_mul_f32_e32 v88, v88, v186
	v_mul_f32_e32 v89, v89, v186
	v_mul_f32_e32 v90, v90, v186
	v_mul_f32_e32 v91, v91, v186
	v_pk_mul_f32 v[88:89], v[164:165], v[88:89]
	v_pk_mul_f32 v[90:91], v[166:167], v[90:91]
	v_pk_fma_f32 v[88:89], v[180:181], v[88:89], v[204:205]
	v_pk_fma_f32 v[90:91], v[182:183], v[90:91], v[206:207]
	v_cvt_pk_bf16_f32 v88, v88, v89
	v_cvt_pk_bf16_f32 v89, v90, v91
	global_store_dwordx2 v[142:143], v[88:89], off offset:288
	s_mov_b64 s[4:5], 0x18000
	v_lshl_add_u64 v[142:143], v[144:145], 0, s[4:5]
	v_mul_f32_e32 v106, v106, v187
	v_mul_f32_e32 v107, v107, v187
	v_mul_f32_e32 v108, v108, v187
	v_mul_f32_e32 v109, v109, v187
	v_pk_mul_f32 v[106:107], v[152:153], v[106:107]
	v_pk_mul_f32 v[108:109], v[154:155], v[108:109]
	v_pk_fma_f32 v[106:107], v[168:169], v[106:107], v[192:193]
	v_pk_fma_f32 v[108:109], v[170:171], v[108:109], v[194:195]
	v_cvt_pk_bf16_f32 v106, v106, v107
	v_cvt_pk_bf16_f32 v107, v108, v109
	global_store_dwordx2 v[142:143], v[106:107], off
	v_mul_f32_e32 v8, v8, v187
	v_mul_f32_e32 v9, v9, v187
	v_mul_f32_e32 v10, v10, v187
	v_mul_f32_e32 v11, v11, v187
	v_pk_mul_f32 v[8:9], v[156:157], v[8:9]
	v_pk_mul_f32 v[10:11], v[158:159], v[10:11]
	v_pk_fma_f32 v[8:9], v[172:173], v[8:9], v[196:197]
	v_pk_fma_f32 v[10:11], v[174:175], v[10:11], v[198:199]
	v_cvt_pk_bf16_f32 v8, v8, v9
	v_cvt_pk_bf16_f32 v9, v10, v11
	global_store_dwordx2 v[142:143], v[8:9], off offset:32
	v_mul_f32_e32 v44, v44, v187
	v_mul_f32_e32 v45, v45, v187
	v_mul_f32_e32 v46, v46, v187
	v_mul_f32_e32 v47, v47, v187
	v_pk_mul_f32 v[44:45], v[160:161], v[44:45]
	v_pk_mul_f32 v[46:47], v[162:163], v[46:47]
	v_pk_fma_f32 v[44:45], v[176:177], v[44:45], v[200:201]
	v_pk_fma_f32 v[46:47], v[178:179], v[46:47], v[202:203]
	v_cvt_pk_bf16_f32 v44, v44, v45
	v_cvt_pk_bf16_f32 v45, v46, v47
	global_store_dwordx2 v[142:143], v[44:45], off offset:256
	v_mul_f32_e32 v16, v16, v187
	v_mul_f32_e32 v17, v17, v187
	v_mul_f32_e32 v18, v18, v187
	v_mul_f32_e32 v19, v19, v187
	v_pk_mul_f32 v[16:17], v[164:165], v[16:17]
	v_pk_mul_f32 v[18:19], v[166:167], v[18:19]
	v_pk_fma_f32 v[16:17], v[180:181], v[16:17], v[204:205]
	v_pk_fma_f32 v[18:19], v[182:183], v[18:19], v[206:207]
	v_cvt_pk_bf16_f32 v16, v16, v17
	v_cvt_pk_bf16_f32 v17, v18, v19
	global_store_dwordx2 v[142:143], v[16:17], off offset:288
	s_mov_b64 s[4:5], 0x40000
	v_lshl_add_u64 v[142:143], v[144:145], 0, s[4:5]
	v_mul_f32_e32 v84, v84, v188
	v_mul_f32_e32 v85, v85, v188
	v_mul_f32_e32 v86, v86, v188
	v_mul_f32_e32 v87, v87, v188
	v_pk_mul_f32 v[84:85], v[152:153], v[84:85]
	v_pk_mul_f32 v[86:87], v[154:155], v[86:87]
	v_pk_fma_f32 v[84:85], v[168:169], v[84:85], v[192:193]
	v_pk_fma_f32 v[86:87], v[170:171], v[86:87], v[194:195]
	v_cvt_pk_bf16_f32 v84, v84, v85
	v_cvt_pk_bf16_f32 v85, v86, v87
	global_store_dwordx2 v[142:143], v[84:85], off
	v_mul_f32_e32 v20, v20, v188
	v_mul_f32_e32 v21, v21, v188
	v_mul_f32_e32 v22, v22, v188
	v_mul_f32_e32 v23, v23, v188
	v_pk_mul_f32 v[20:21], v[156:157], v[20:21]
	v_pk_mul_f32 v[22:23], v[158:159], v[22:23]
	v_pk_fma_f32 v[20:21], v[172:173], v[20:21], v[196:197]
	v_pk_fma_f32 v[22:23], v[174:175], v[22:23], v[198:199]
	v_cvt_pk_bf16_f32 v20, v20, v21
	v_cvt_pk_bf16_f32 v21, v22, v23
	global_store_dwordx2 v[142:143], v[20:21], off offset:32
	v_mul_f32_e32 v40, v40, v188
	v_mul_f32_e32 v41, v41, v188
	v_mul_f32_e32 v42, v42, v188
	v_mul_f32_e32 v43, v43, v188
	v_pk_mul_f32 v[40:41], v[160:161], v[40:41]
	v_pk_mul_f32 v[42:43], v[162:163], v[42:43]
	v_pk_fma_f32 v[40:41], v[176:177], v[40:41], v[200:201]
	v_pk_fma_f32 v[42:43], v[178:179], v[42:43], v[202:203]
	v_cvt_pk_bf16_f32 v40, v40, v41
	v_cvt_pk_bf16_f32 v41, v42, v43
	global_store_dwordx2 v[142:143], v[40:41], off offset:256
	v_mul_f32_e32 v28, v28, v188
	v_mul_f32_e32 v29, v29, v188
	v_mul_f32_e32 v30, v30, v188
; __device__ __forceinline__ unsigned pk2(float lo, float hi) { unsigned r; asm volatile("v_cvt_pk_bf16_f32 %0, %1, %2" : "=v"(r) : "v"(lo), "v"(hi)); return r; }
; #define GAS __attribute__((address_space(1)))
; __device__ void phase_norm(const Params& p, int l, int which) {
;     ...
; #pragma unroll
;         for (int j = 0; j < 4; ++j) {
;             const f32x4 y = v[j] * rstd * g4[j] * (s4[j] + 1.f) + h4[j];
;             u32x2 o; o.x = pk2(y.x, y.y); o.y = pk2(y.z, y.w);
;             ((GAS u32x2*)(H + (size_t)row * DM))[lane + 64 * j] = o;
;         }
	v_mul_f32_e32 v31, v31, v188
	v_pk_mul_f32 v[28:29], v[164:165], v[28:29]
	v_pk_mul_f32 v[30:31], v[166:167], v[30:31]
	v_pk_fma_f32 v[28:29], v[180:181], v[28:29], v[204:205]
	v_pk_fma_f32 v[30:31], v[182:183], v[30:31], v[206:207]
	v_cvt_pk_bf16_f32 v28, v28, v29
	v_cvt_pk_bf16_f32 v29, v30, v31
	global_store_dwordx2 v[142:143], v[28:29], off offset:288
	s_mov_b64 s[4:5], 0x48000
	v_lshl_add_u64 v[142:143], v[144:145], 0, s[4:5]
	v_mul_f32_e32 v80, v80, v189
	v_mul_f32_e32 v81, v81, v189
	v_mul_f32_e32 v82, v82, v189
	v_mul_f32_e32 v83, v83, v189
	v_pk_mul_f32 v[80:81], v[152:153], v[80:81]
	v_pk_mul_f32 v[82:83], v[154:155], v[82:83]
	v_pk_fma_f32 v[80:81], v[168:169], v[80:81], v[192:193]
	v_pk_fma_f32 v[82:83], v[170:171], v[82:83], v[194:195]
	v_cvt_pk_bf16_f32 v80, v80, v81
	v_cvt_pk_bf16_f32 v81, v82, v83
	global_store_dwordx2 v[142:143], v[80:81], off
	v_mul_f32_e32 v76, v76, v189
	v_mul_f32_e32 v77, v77, v189
	v_mul_f32_e32 v78, v78, v189
	v_mul_f32_e32 v79, v79, v189
	v_pk_mul_f32 v[76:77], v[156:157], v[76:77]
	v_pk_mul_f32 v[78:79], v[158:159], v[78:79]
	v_pk_fma_f32 v[76:77], v[172:173], v[76:77], v[196:197]
	v_pk_fma_f32 v[78:79], v[174:175], v[78:79], v[198:199]
	v_cvt_pk_bf16_f32 v76, v76, v77
	v_cvt_pk_bf16_f32 v77, v78, v79
	global_store_dwordx2 v[142:143], v[76:77], off offset:32
	v_mul_f32_e32 v60, v60, v189
	v_mul_f32_e32 v61, v61, v189
	v_mul_f32_e32 v62, v62, v189
	v_mul_f32_e32 v63, v63, v189
	v_pk_mul_f32 v[60:61], v[160:161], v[60:61]
	v_pk_mul_f32 v[62:63], v[162:163], v[62:63]
	v_pk_fma_f32 v[60:61], v[176:177], v[60:61], v[200:201]
	v_pk_fma_f32 v[62:63], v[178:179], v[62:63], v[202:203]
	v_cvt_pk_bf16_f32 v60, v60, v61
	v_cvt_pk_bf16_f32 v61, v62, v63
	global_store_dwordx2 v[142:143], v[60:61], off offset:256
	v_mul_f32_e32 v56, v56, v189
	v_mul_f32_e32 v57, v57, v189
	v_mul_f32_e32 v58, v58, v189
	v_mul_f32_e32 v59, v59, v189
	v_pk_mul_f32 v[56:57], v[164:165], v[56:57]
	v_pk_mul_f32 v[58:59], v[166:167], v[58:59]
	v_pk_fma_f32 v[56:57], v[180:181], v[56:57], v[204:205]
	v_pk_fma_f32 v[58:59], v[182:183], v[58:59], v[206:207]
	v_cvt_pk_bf16_f32 v56, v56, v57
	v_cvt_pk_bf16_f32 v57, v58, v59
	global_store_dwordx2 v[142:143], v[56:57], off offset:288
	s_mov_b64 s[4:5], 0x50000
	v_lshl_add_u64 v[142:143], v[144:145], 0, s[4:5]
	v_mul_f32_e32 v72, v72, v190
	v_mul_f32_e32 v73, v73, v190
	v_mul_f32_e32 v74, v74, v190
	v_mul_f32_e32 v75, v75, v190
	v_pk_mul_f32 v[72:73], v[152:153], v[72:73]
	v_pk_mul_f32 v[74:75], v[154:155], v[74:75]
	v_pk_fma_f32 v[72:73], v[168:169], v[72:73], v[192:193]
	v_pk_fma_f32 v[74:75], v[170:171], v[74:75], v[194:195]
	v_cvt_pk_bf16_f32 v72, v72, v73
	v_cvt_pk_bf16_f32 v73, v74, v75
	global_store_dwordx2 v[142:143], v[72:73], off
	v_mul_f32_e32 v68, v68, v190
	v_mul_f32_e32 v69, v69, v190
	v_mul_f32_e32 v70, v70, v190
	v_mul_f32_e32 v71, v71, v190
	v_pk_mul_f32 v[68:69], v[156:157], v[68:69]
	v_pk_mul_f32 v[70:71], v[158:159], v[70:71]
	v_pk_fma_f32 v[68:69], v[172:173], v[68:69], v[196:197]
	v_pk_fma_f32 v[70:71], v[174:175], v[70:71], v[198:199]
	v_cvt_pk_bf16_f32 v68, v68, v69
	v_cvt_pk_bf16_f32 v69, v70, v71
	global_store_dwordx2 v[142:143], v[68:69], off offset:32
	v_mul_f32_e32 v52, v52, v190
	v_mul_f32_e32 v53, v53, v190
	v_mul_f32_e32 v54, v54, v190
	v_mul_f32_e32 v55, v55, v190
	v_pk_mul_f32 v[52:53], v[160:161], v[52:53]
	v_pk_mul_f32 v[54:55], v[162:163], v[54:55]
	v_pk_fma_f32 v[52:53], v[176:177], v[52:53], v[200:201]
	v_pk_fma_f32 v[54:55], v[178:179], v[54:55], v[202:203]
	v_cvt_pk_bf16_f32 v52, v52, v53
	v_cvt_pk_bf16_f32 v53, v54, v55
	global_store_dwordx2 v[142:143], v[52:53], off offset:256
	v_mul_f32_e32 v0, v0, v190
	v_mul_f32_e32 v1, v1, v190
	v_mul_f32_e32 v2, v2, v190
	v_mul_f32_e32 v3, v3, v190
	v_pk_mul_f32 v[0:1], v[164:165], v[0:1]
	v_pk_mul_f32 v[2:3], v[166:167], v[2:3]
	v_pk_fma_f32 v[0:1], v[180:181], v[0:1], v[204:205]
	v_pk_fma_f32 v[2:3], v[182:183], v[2:3], v[206:207]
	v_cvt_pk_bf16_f32 v0, v0, v1
	v_cvt_pk_bf16_f32 v1, v2, v3
	global_store_dwordx2 v[142:143], v[0:1], off offset:288
	s_mov_b64 s[4:5], 0x58000
	v_lshl_add_u64 v[142:143], v[144:145], 0, s[4:5]
	v_mul_f32_e32 v64, v64, v191
	v_mul_f32_e32 v65, v65, v191
	v_mul_f32_e32 v66, v66, v191
	v_mul_f32_e32 v67, v67, v191
	v_pk_mul_f32 v[64:65], v[152:153], v[64:65]
	v_pk_mul_f32 v[66:67], v[154:155], v[66:67]
	v_pk_fma_f32 v[64:65], v[168:169], v[64:65], v[192:193]
	v_pk_fma_f32 v[66:67], v[170:171], v[66:67], v[194:195]
	v_cvt_pk_bf16_f32 v64, v64, v65
	v_cvt_pk_bf16_f32 v65, v66, v67
	global_store_dwordx2 v[142:143], v[64:65], off
	v_mul_f32_e32 v24, v24, v191
	v_mul_f32_e32 v25, v25, v191
	v_mul_f32_e32 v26, v26, v191
	v_mul_f32_e32 v27, v27, v191
	v_pk_mul_f32 v[24:25], v[156:157], v[24:25]
	v_pk_mul_f32 v[26:27], v[158:159], v[26:27]
	v_pk_fma_f32 v[24:25], v[172:173], v[24:25], v[196:197]
	v_pk_fma_f32 v[26:27], v[174:175], v[26:27], v[198:199]
	v_cvt_pk_bf16_f32 v24, v24, v25
	v_cvt_pk_bf16_f32 v25, v26, v27
	global_store_dwordx2 v[142:143], v[24:25], off offset:32
	v_mul_f32_e32 v36, v36, v191
	v_mul_f32_e32 v37, v37, v191
	v_mul_f32_e32 v38, v38, v191
	v_mul_f32_e32 v39, v39, v191
	v_pk_mul_f32 v[36:37], v[160:161], v[36:37]
	v_pk_mul_f32 v[38:39], v[162:163], v[38:39]
	v_pk_fma_f32 v[36:37], v[176:177], v[36:37], v[200:201]
	v_pk_fma_f32 v[38:39], v[178:179], v[38:39], v[202:203]
	v_cvt_pk_bf16_f32 v36, v36, v37
	v_cvt_pk_bf16_f32 v37, v38, v39
	global_store_dwordx2 v[142:143], v[36:37], off offset:256
	v_mul_f32_e32 v32, v32, v191
	v_mul_f32_e32 v33, v33, v191
	v_mul_f32_e32 v34, v34, v191
	v_mul_f32_e32 v35, v35, v191
	v_pk_mul_f32 v[32:33], v[164:165], v[32:33]
	v_pk_mul_f32 v[34:35], v[166:167], v[34:35]
	v_pk_fma_f32 v[32:33], v[180:181], v[32:33], v[204:205]
	v_pk_fma_f32 v[34:35], v[182:183], v[34:35], v[206:207]
	v_cvt_pk_bf16_f32 v32, v32, v33
	v_cvt_pk_bf16_f32 v33, v34, v35
	global_store_dwordx2 v[142:143], v[32:33], off offset:288
.Lmy_fn_done:
	s_nop 3
	s_cmp_lg_u32 s98, 1
	s_cbranch_scc1 .Lmy_fn_e1
	s_barrier

; __device__ __forceinline__ int otid() { int t = threadIdx.x; asm volatile("" : "+v"(t)); return t; }
; #define GAS __attribute__((address_space(1)))
; __device__ __forceinline__ float wave_sum(float v) {
; #pragma unroll
;     for (int o = 1; o < 64; o <<= 1) v += __shfl_xor(v, o);
;     return v;
; }
; __device__ void phase_final(const Params& p) {
;     const int tid = otid(), lane = tid & 63, gw = blockIdx.x * 8 + (tid >> 6), nw = gridDim.x * 8;
;     GAS const f32x4* gf = (GAS const f32x4*)(unsigned long long)p.norm_final;
;     for (int row = gw; row < NL; row += nw) {
;         GAS f32x4* xr = (GAS f32x4*)(unsigned long long)(p.out + (size_t)row * DM);
;         f32x4 v[4], g4[4];
; #pragma unroll
;         for (int j = 0; j < 4; ++j) { v[j] = xr[lane + 64 * j]; g4[j] = gf[lane + 64 * j]; }
;         asm volatile("" ::: "memory");
;         float s = 0.f;
; #pragma unroll
;         for (int j = 0; j < 4; ++j) s += (v[j].x * v[j].x + v[j].y * v[j].y) + (v[j].z * v[j].z + v[j].w * v[j].w);
;         const float rstd = rsqrtf(wave_sum(s) * (1.f / 1024.f) + 1e-6f);
; #pragma unroll
;         for (int j = 0; j < 4; ++j) xr[lane + 64 * j] = v[j] * rstd * g4[j];
;     }
; }
.LBB0_647:
	s_cmpk_lg_u32 s72, 0x100
	s_cbranch_scc1 .Lmy_fn_generic
	global_load_dwordx4 v[0:3], v[34:35], off
	global_load_dwordx4 v[8:11], v[34:35], off offset:1024
	global_load_dwordx4 v[16:19], v[34:35], off offset:2048
	global_load_dwordx4 v[28:31], v[34:35], off offset:3072
	v_lshl_add_u64 v[180:181], v[36:37], 0, v[96:97]
	global_load_dwordx4 v[100:103], v[180:181], off
	global_load_dwordx4 v[104:107], v[180:181], off offset:1024
	global_load_dwordx4 v[108:111], v[180:181], off offset:2048
	global_load_dwordx4 v[112:115], v[180:181], off offset:3072
	v_lshl_add_u64 v[36:37], v[36:37], 0, s[60:61]
	v_lshl_add_u64 v[182:183], v[36:37], 0, v[96:97]
	global_load_dwordx4 v[116:119], v[182:183], off
	global_load_dwordx4 v[120:123], v[182:183], off offset:1024
	global_load_dwordx4 v[124:127], v[182:183], off offset:2048
	global_load_dwordx4 v[128:131], v[182:183], off offset:3072
	v_lshl_add_u64 v[36:37], v[36:37], 0, s[60:61]
	v_lshl_add_u64 v[184:185], v[36:37], 0, v[96:97]
	global_load_dwordx4 v[132:135], v[184:185], off
	global_load_dwordx4 v[136:139], v[184:185], off offset:1024
	global_load_dwordx4 v[140:143], v[184:185], off offset:2048
	global_load_dwordx4 v[144:147], v[184:185], off offset:3072
	v_lshl_add_u64 v[36:37], v[36:37], 0, s[60:61]
	v_lshl_add_u64 v[186:187], v[36:37], 0, v[96:97]
	global_load_dwordx4 v[148:151], v[186:187], off
	global_load_dwordx4 v[152:155], v[186:187], off offset:1024
	global_load_dwordx4 v[156:159], v[186:187], off offset:2048
	global_load_dwordx4 v[160:163], v[186:187], off offset:3072
	v_lshl_add_u64 v[36:37], v[36:37], 0, s[60:61]
	s_waitcnt vmcnt(12)
	v_pk_mul_f32 v[40:41], v[102:103], v[102:103]
	v_pk_mul_f32 v[42:43], v[100:101], v[100:101]
	v_mul_f32_e32 v33, v112, v112
	v_pk_mov_b32 v[44:45], v[42:43], v[40:41] op_sel:[1,0]
	v_mov_b32_e32 v43, v41
	v_pk_add_f32 v[40:41], v[44:45], v[42:43]
	v_pk_mul_f32 v[42:43], v[106:107], v[106:107]
	v_pk_mul_f32 v[44:45], v[104:105], v[104:105]
	v_pk_add_f32 v[40:41], v[40:41], v[40:41] op_sel:[0,1] op_sel_hi:[1,0]
	v_pk_mov_b32 v[46:47], v[44:45], v[42:43] op_sel:[1,0]
	v_mov_b32_e32 v45, v43
	v_pk_add_f32 v[42:43], v[46:47], v[44:45]
	v_mul_f32_e32 v44, v113, v113
	v_pk_add_f32 v[42:43], v[42:43], v[42:43] op_sel:[0,1] op_sel_hi:[1,0]
	v_mov_b32_e32 v41, v33
	v_mov_b32_e32 v43, v44
	v_pk_add_f32 v[40:41], v[40:41], v[42:43]
	v_mul_f32_e32 v42, v109, v109
	v_mul_f32_e32 v45, v114, v114
	v_pk_fma_f32 v[42:43], v[108:109], v[108:109], v[42:43] op_sel_hi:[1,1,0]
	v_mul_f32_e32 v44, v111, v111
	v_mul_f32_e32 v46, v115, v115
	v_mov_b32_e32 v43, v45
	v_pk_fma_f32 v[44:45], v[110:111], v[110:111], v[44:45] op_sel_hi:[1,1,0]
	s_nop 0
	v_mov_b32_e32 v45, v46
	v_pk_add_f32 v[42:43], v[42:43], v[44:45]
	s_nop 0
	v_pk_add_f32 v[40:41], v[40:41], v[42:43]
	s_nop 0
	v_add_f32_e32 v33, v40, v41
	v_and_b32_e32 v40, 64, v236
	v_add_u32_e32 v40, 64, v40
	v_xor_b32_e32 v41, 1, v236
	v_cmp_lt_i32_e32 vcc, v41, v40
	s_nop 1
	v_cndmask_b32_e32 v41, v236, v41, vcc
	v_lshlrev_b32_e32 v41, 2, v41
	ds_bpermute_b32 v41, v41, v33
	s_waitcnt lgkmcnt(0)
	v_add_f32_e32 v33, v33, v41
	v_xor_b32_e32 v41, 2, v236
	v_cmp_lt_i32_e32 vcc, v41, v40
	s_nop 1
	v_cndmask_b32_e32 v41, v236, v41, vcc
	v_lshlrev_b32_e32 v41, 2, v41
	ds_bpermute_b32 v41, v41, v33
	s_waitcnt lgkmcnt(0)
	v_add_f32_e32 v33, v33, v41
	v_xor_b32_e32 v41, 4, v236
	v_cmp_lt_i32_e32 vcc, v41, v40
	s_nop 1
	v_cndmask_b32_e32 v41, v236, v41, vcc
	v_lshlrev_b32_e32 v41, 2, v41
	ds_bpermute_b32 v41, v41, v33
	s_waitcnt lgkmcnt(0)
	v_add_f32_e32 v33, v33, v41
	v_xor_b32_e32 v41, 8, v236
	v_cmp_lt_i32_e32 vcc, v41, v40
	s_nop 1
	v_cndmask_b32_e32 v41, v236, v41, vcc
	v_lshlrev_b32_e32 v41, 2, v41
	ds_bpermute_b32 v41, v41, v33
	s_waitcnt lgkmcnt(0)
	v_add_f32_e32 v33, v33, v41
	v_xor_b32_e32 v41, 16, v236
	v_cmp_lt_i32_e32 vcc, v41, v40
	s_nop 1
	v_cndmask_b32_e32 v41, v236, v41, vcc
	v_lshlrev_b32_e32 v41, 2, v41
	ds_bpermute_b32 v41, v41, v33
	s_waitcnt lgkmcnt(0)
	v_add_f32_e32 v33, v33, v41
	v_xor_b32_e32 v41, 32, v236
	v_cmp_lt_i32_e32 vcc, v41, v40
	s_nop 1
	v_cndmask_b32_e32 v40, v236, v41, vcc
	v_lshlrev_b32_e32 v40, 2, v40
	ds_bpermute_b32 v40, v40, v33
	s_waitcnt lgkmcnt(0)
	v_add_f32_e32 v33, v33, v40
	v_fmamk_f32 v33, v33, 0x3a800000, v233
	v_cmp_gt_f32_e32 vcc, s58, v33
	v_mul_f32_e32 v40, 0x4b800000, v33
	s_nop 0
	v_cndmask_b32_e32 v33, v33, v40, vcc
	v_rsq_f32_e32 v33, v33
	s_nop 0
	v_mul_f32_e32 v40, 0x45800000, v33
	v_cndmask_b32_e32 v40, v33, v40, vcc
	v_pk_mul_f32 v[164:165], v[100:101], v[40:41] op_sel_hi:[1,0]
	v_pk_mul_f32 v[166:167], v[102:103], v[40:41] op_sel_hi:[1,0]
	v_pk_mul_f32 v[164:165], v[0:1], v[164:165]
	v_pk_mul_f32 v[166:167], v[2:3], v[166:167]
	global_store_dwordx4 v[180:181], v[164:167], off
	v_pk_mul_f32 v[168:169], v[104:105], v[40:41] op_sel_hi:[1,0]
	v_pk_mul_f32 v[170:171], v[106:107], v[40:41] op_sel_hi:[1,0]
	v_pk_mul_f32 v[168:169], v[8:9], v[168:169]
	v_pk_mul_f32 v[170:171], v[10:11], v[170:171]
	global_store_dwordx4 v[180:181], v[168:171], off offset:1024
	v_pk_mul_f32 v[172:173], v[108:109], v[40:41] op_sel_hi:[1,0]
	v_pk_mul_f32 v[174:175], v[110:111], v[40:41] op_sel_hi:[1,0]
	v_pk_mul_f32 v[172:173], v[16:17], v[172:173]
	v_pk_mul_f32 v[174:175], v[18:19], v[174:175]
	global_store_dwordx4 v[180:181], v[172:175], off offset:2048
	v_pk_mul_f32 v[176:177], v[112:113], v[40:41] op_sel_hi:[1,0]
	v_pk_mul_f32 v[178:179], v[114:115], v[40:41] op_sel_hi:[1,0]
	v_pk_mul_f32 v[176:177], v[28:29], v[176:177]
	v_pk_mul_f32 v[178:179], v[30:31], v[178:179]
	global_store_dwordx4 v[180:181], v[176:179], off offset:3072
	v_lshl_add_u64 v[180:181], v[36:37], 0, v[96:97]
	global_load_dwordx4 v[100:103], v[180:181], off
	global_load_dwordx4 v[104:107], v[180:181], off offset:1024
	global_load_dwordx4 v[108:111], v[180:181], off offset:2048
	global_load_dwordx4 v[112:115], v[180:181], off offset:3072
	v_lshl_add_u64 v[36:37], v[36:37], 0, s[60:61]
	s_waitcnt vmcnt(16)
; __device__ __forceinline__ int otid() { int t = threadIdx.x; asm volatile("" : "+v"(t)); return t; }
; #define GAS __attribute__((address_space(1)))
; __device__ __forceinline__ float wave_sum(float v) {
; #pragma unroll
;     for (int o = 1; o < 64; o <<= 1) v += __shfl_xor(v, o);
;     return v;
; }
; __device__ void phase_final(const Params& p) {
;     const int tid = otid(), lane = tid & 63, gw = blockIdx.x * 8 + (tid >> 6), nw = gridDim.x * 8;
;     GAS const f32x4* gf = (GAS const f32x4*)(unsigned long long)p.norm_final;
;     for (int row = gw; row < NL; row += nw) {
;         GAS f32x4* xr = (GAS f32x4*)(unsigned long long)(p.out + (size_t)row * DM);
;         f32x4 v[4], g4[4];
; #pragma unroll
;         for (int j = 0; j < 4; ++j) { v[j] = xr[lane + 64 * j]; g4[j] = gf[lane + 64 * j]; }
;         asm volatile("" ::: "memory");
;         float s = 0.f;
; #pragma unroll
;         for (int j = 0; j < 4; ++j) s += (v[j].x * v[j].x + v[j].y * v[j].y) + (v[j].z * v[j].z + v[j].w * v[j].w);
;         const float rstd = rsqrtf(wave_sum(s) * (1.f / 1024.f) + 1e-6f);
; #pragma unroll
;         for (int j = 0; j < 4; ++j) xr[lane + 64 * j] = v[j] * rstd * g4[j];
;     }
; }
	v_pk_mul_f32 v[40:41], v[118:119], v[118:119]
	v_pk_mul_f32 v[42:43], v[116:117], v[116:117]
	v_mul_f32_e32 v33, v128, v128
	v_pk_mov_b32 v[44:45], v[42:43], v[40:41] op_sel:[1,0]
	v_mov_b32_e32 v43, v41
	v_pk_add_f32 v[40:41], v[44:45], v[42:43]
	v_pk_mul_f32 v[42:43], v[122:123], v[122:123]
	v_pk_mul_f32 v[44:45], v[120:121], v[120:121]
	v_pk_add_f32 v[40:41], v[40:41], v[40:41] op_sel:[0,1] op_sel_hi:[1,0]
	v_pk_mov_b32 v[46:47], v[44:45], v[42:43] op_sel:[1,0]
	v_mov_b32_e32 v45, v43
	v_pk_add_f32 v[42:43], v[46:47], v[44:45]
	v_mul_f32_e32 v44, v129, v129
	v_pk_add_f32 v[42:43], v[42:43], v[42:43] op_sel:[0,1] op_sel_hi:[1,0]
	v_mov_b32_e32 v41, v33
	v_mov_b32_e32 v43, v44
	v_pk_add_f32 v[40:41], v[40:41], v[42:43]
	v_mul_f32_e32 v42, v125, v125
	v_mul_f32_e32 v45, v130, v130
	v_pk_fma_f32 v[42:43], v[124:125], v[124:125], v[42:43] op_sel_hi:[1,1,0]
	v_mul_f32_e32 v44, v127, v127
	v_mul_f32_e32 v46, v131, v131
	v_mov_b32_e32 v43, v45
	v_pk_fma_f32 v[44:45], v[126:127], v[126:127], v[44:45] op_sel_hi:[1,1,0]
	s_nop 0
	v_mov_b32_e32 v45, v46
	v_pk_add_f32 v[42:43], v[42:43], v[44:45]
	s_nop 0
	v_pk_add_f32 v[40:41], v[40:41], v[42:43]
	s_nop 0
	v_add_f32_e32 v33, v40, v41
	v_and_b32_e32 v40, 64, v236
	v_add_u32_e32 v40, 64, v40
	v_xor_b32_e32 v41, 1, v236
	v_cmp_lt_i32_e32 vcc, v41, v40
	s_nop 1
	v_cndmask_b32_e32 v41, v236, v41, vcc
	v_lshlrev_b32_e32 v41, 2, v41
	ds_bpermute_b32 v41, v41, v33
	s_waitcnt lgkmcnt(0)
	v_add_f32_e32 v33, v33, v41
	v_xor_b32_e32 v41, 2, v236
	v_cmp_lt_i32_e32 vcc, v41, v40
	s_nop 1
	v_cndmask_b32_e32 v41, v236, v41, vcc
	v_lshlrev_b32_e32 v41, 2, v41
	ds_bpermute_b32 v41, v41, v33
	s_waitcnt lgkmcnt(0)
	v_add_f32_e32 v33, v33, v41
	v_xor_b32_e32 v41, 4, v236
	v_cmp_lt_i32_e32 vcc, v41, v40
	s_nop 1
	v_cndmask_b32_e32 v41, v236, v41, vcc
	v_lshlrev_b32_e32 v41, 2, v41
	ds_bpermute_b32 v41, v41, v33
	s_waitcnt lgkmcnt(0)
	v_add_f32_e32 v33, v33, v41
	v_xor_b32_e32 v41, 8, v236
	v_cmp_lt_i32_e32 vcc, v41, v40
	s_nop 1
	v_cndmask_b32_e32 v41, v236, v41, vcc
	v_lshlrev_b32_e32 v41, 2, v41
	ds_bpermute_b32 v41, v41, v33
	s_waitcnt lgkmcnt(0)
	v_add_f32_e32 v33, v33, v41
	v_xor_b32_e32 v41, 16, v236
	v_cmp_lt_i32_e32 vcc, v41, v40
	s_nop 1
	v_cndmask_b32_e32 v41, v236, v41, vcc
	v_lshlrev_b32_e32 v41, 2, v41
	ds_bpermute_b32 v41, v41, v33
	s_waitcnt lgkmcnt(0)
	v_add_f32_e32 v33, v33, v41
	v_xor_b32_e32 v41, 32, v236
	v_cmp_lt_i32_e32 vcc, v41, v40
	s_nop 1
	v_cndmask_b32_e32 v40, v236, v41, vcc
	v_lshlrev_b32_e32 v40, 2, v40
	ds_bpermute_b32 v40, v40, v33
	s_waitcnt lgkmcnt(0)
	v_add_f32_e32 v33, v33, v40
	v_fmamk_f32 v33, v33, 0x3a800000, v233
	v_cmp_gt_f32_e32 vcc, s58, v33
	v_mul_f32_e32 v40, 0x4b800000, v33
	s_nop 0
	v_cndmask_b32_e32 v33, v33, v40, vcc
	v_rsq_f32_e32 v33, v33
	s_nop 0
	v_mul_f32_e32 v40, 0x45800000, v33
	v_cndmask_b32_e32 v40, v33, v40, vcc
	v_pk_mul_f32 v[164:165], v[116:117], v[40:41] op_sel_hi:[1,0]
	v_pk_mul_f32 v[166:167], v[118:119], v[40:41] op_sel_hi:[1,0]
	v_pk_mul_f32 v[164:165], v[0:1], v[164:165]
	v_pk_mul_f32 v[166:167], v[2:3], v[166:167]
	global_store_dwordx4 v[182:183], v[164:167], off
	v_pk_mul_f32 v[168:169], v[120:121], v[40:41] op_sel_hi:[1,0]
	v_pk_mul_f32 v[170:171], v[122:123], v[40:41] op_sel_hi:[1,0]
	v_pk_mul_f32 v[168:169], v[8:9], v[168:169]
	v_pk_mul_f32 v[170:171], v[10:11], v[170:171]
	global_store_dwordx4 v[182:183], v[168:171], off offset:1024
	v_pk_mul_f32 v[172:173], v[124:125], v[40:41] op_sel_hi:[1,0]
	v_pk_mul_f32 v[174:175], v[126:127], v[40:41] op_sel_hi:[1,0]
	v_pk_mul_f32 v[172:173], v[16:17], v[172:173]
	v_pk_mul_f32 v[174:175], v[18:19], v[174:175]
	global_store_dwordx4 v[182:183], v[172:175], off offset:2048
	v_pk_mul_f32 v[176:177], v[128:129], v[40:41] op_sel_hi:[1,0]
	v_pk_mul_f32 v[178:179], v[130:131], v[40:41] op_sel_hi:[1,0]
	v_pk_mul_f32 v[176:177], v[28:29], v[176:177]
	v_pk_mul_f32 v[178:179], v[30:31], v[178:179]
	global_store_dwordx4 v[182:183], v[176:179], off offset:3072
	v_lshl_add_u64 v[182:183], v[36:37], 0, v[96:97]
	global_load_dwordx4 v[116:119], v[182:183], off
	global_load_dwordx4 v[120:123], v[182:183], off offset:1024
	global_load_dwordx4 v[124:127], v[182:183], off offset:2048
	global_load_dwordx4 v[128:131], v[182:183], off offset:3072
	v_lshl_add_u64 v[36:37], v[36:37], 0, s[60:61]
	s_waitcnt vmcnt(20)
	v_pk_mul_f32 v[40:41], v[134:135], v[134:135]
	v_pk_mul_f32 v[42:43], v[132:133], v[132:133]
	v_mul_f32_e32 v33, v144, v144
	v_pk_mov_b32 v[44:45], v[42:43], v[40:41] op_sel:[1,0]
	v_mov_b32_e32 v43, v41
	v_pk_add_f32 v[40:41], v[44:45], v[42:43]
	v_pk_mul_f32 v[42:43], v[138:139], v[138:139]
	v_pk_mul_f32 v[44:45], v[136:137], v[136:137]
	v_pk_add_f32 v[40:41], v[40:41], v[40:41] op_sel:[0,1] op_sel_hi:[1,0]
	v_pk_mov_b32 v[46:47], v[44:45], v[42:43] op_sel:[1,0]
	v_mov_b32_e32 v45, v43
	v_pk_add_f32 v[42:43], v[46:47], v[44:45]
	v_mul_f32_e32 v44, v145, v145
	v_pk_add_f32 v[42:43], v[42:43], v[42:43] op_sel:[0,1] op_sel_hi:[1,0]
	v_mov_b32_e32 v41, v33
	v_mov_b32_e32 v43, v44
	v_pk_add_f32 v[40:41], v[40:41], v[42:43]
	v_mul_f32_e32 v42, v141, v141
	v_mul_f32_e32 v45, v146, v146
	v_pk_fma_f32 v[42:43], v[140:141], v[140:141], v[42:43] op_sel_hi:[1,1,0]
	v_mul_f32_e32 v44, v143, v143
	v_mul_f32_e32 v46, v147, v147
	v_mov_b32_e32 v43, v45
	v_pk_fma_f32 v[44:45], v[142:143], v[142:143], v[44:45] op_sel_hi:[1,1,0]
	s_nop 0
	v_mov_b32_e32 v45, v46
	v_pk_add_f32 v[42:43], v[42:43], v[44:45]
	s_nop 0
	v_pk_add_f32 v[40:41], v[40:41], v[42:43]
	s_nop 0
	v_add_f32_e32 v33, v40, v41
	v_and_b32_e32 v40, 64, v236
	v_add_u32_e32 v40, 64, v40
	v_xor_b32_e32 v41, 1, v236
	v_cmp_lt_i32_e32 vcc, v41, v40
	s_nop 1
	v_cndmask_b32_e32 v41, v236, v41, vcc
	v_lshlrev_b32_e32 v41, 2, v41
	ds_bpermute_b32 v41, v41, v33
	s_waitcnt lgkmcnt(0)
; __device__ __forceinline__ int otid() { int t = threadIdx.x; asm volatile("" : "+v"(t)); return t; }
; #define GAS __attribute__((address_space(1)))
; __device__ __forceinline__ float wave_sum(float v) {
; #pragma unroll
;     for (int o = 1; o < 64; o <<= 1) v += __shfl_xor(v, o);
;     return v;
; }
; __device__ void phase_final(const Params& p) {
;     const int tid = otid(), lane = tid & 63, gw = blockIdx.x * 8 + (tid >> 6), nw = gridDim.x * 8;
;     GAS const f32x4* gf = (GAS const f32x4*)(unsigned long long)p.norm_final;
;     for (int row = gw; row < NL; row += nw) {
;         GAS f32x4* xr = (GAS f32x4*)(unsigned long long)(p.out + (size_t)row * DM);
;         f32x4 v[4], g4[4];
; #pragma unroll
;         for (int j = 0; j < 4; ++j) { v[j] = xr[lane + 64 * j]; g4[j] = gf[lane + 64 * j]; }
;         asm volatile("" ::: "memory");
;         float s = 0.f;
; #pragma unroll
;         for (int j = 0; j < 4; ++j) s += (v[j].x * v[j].x + v[j].y * v[j].y) + (v[j].z * v[j].z + v[j].w * v[j].w);
;         const float rstd = rsqrtf(wave_sum(s) * (1.f / 1024.f) + 1e-6f);
; #pragma unroll
;         for (int j = 0; j < 4; ++j) xr[lane + 64 * j] = v[j] * rstd * g4[j];
;     }
; }
	v_add_f32_e32 v33, v33, v41
	v_xor_b32_e32 v41, 2, v236
	v_cmp_lt_i32_e32 vcc, v41, v40
	s_nop 1
	v_cndmask_b32_e32 v41, v236, v41, vcc
	v_lshlrev_b32_e32 v41, 2, v41
	ds_bpermute_b32 v41, v41, v33
	s_waitcnt lgkmcnt(0)
	v_add_f32_e32 v33, v33, v41
	v_xor_b32_e32 v41, 4, v236
	v_cmp_lt_i32_e32 vcc, v41, v40
	s_nop 1
	v_cndmask_b32_e32 v41, v236, v41, vcc
	v_lshlrev_b32_e32 v41, 2, v41
	ds_bpermute_b32 v41, v41, v33
	s_waitcnt lgkmcnt(0)
	v_add_f32_e32 v33, v33, v41
	v_xor_b32_e32 v41, 8, v236
	v_cmp_lt_i32_e32 vcc, v41, v40
	s_nop 1
	v_cndmask_b32_e32 v41, v236, v41, vcc
	v_lshlrev_b32_e32 v41, 2, v41
	ds_bpermute_b32 v41, v41, v33
	s_waitcnt lgkmcnt(0)
	v_add_f32_e32 v33, v33, v41
	v_xor_b32_e32 v41, 16, v236
	v_cmp_lt_i32_e32 vcc, v41, v40
	s_nop 1
	v_cndmask_b32_e32 v41, v236, v41, vcc
	v_lshlrev_b32_e32 v41, 2, v41
	ds_bpermute_b32 v41, v41, v33
	s_waitcnt lgkmcnt(0)
	v_add_f32_e32 v33, v33, v41
	v_xor_b32_e32 v41, 32, v236
	v_cmp_lt_i32_e32 vcc, v41, v40
	s_nop 1
	v_cndmask_b32_e32 v40, v236, v41, vcc
	v_lshlrev_b32_e32 v40, 2, v40
	ds_bpermute_b32 v40, v40, v33
	s_waitcnt lgkmcnt(0)
	v_add_f32_e32 v33, v33, v40
	v_fmamk_f32 v33, v33, 0x3a800000, v233
	v_cmp_gt_f32_e32 vcc, s58, v33
	v_mul_f32_e32 v40, 0x4b800000, v33
	s_nop 0
	v_cndmask_b32_e32 v33, v33, v40, vcc
	v_rsq_f32_e32 v33, v33
	s_nop 0
	v_mul_f32_e32 v40, 0x45800000, v33
	v_cndmask_b32_e32 v40, v33, v40, vcc
	v_pk_mul_f32 v[164:165], v[132:133], v[40:41] op_sel_hi:[1,0]
	v_pk_mul_f32 v[166:167], v[134:135], v[40:41] op_sel_hi:[1,0]
	v_pk_mul_f32 v[164:165], v[0:1], v[164:165]
	v_pk_mul_f32 v[166:167], v[2:3], v[166:167]
	global_store_dwordx4 v[184:185], v[164:167], off
	v_pk_mul_f32 v[168:169], v[136:137], v[40:41] op_sel_hi:[1,0]
	v_pk_mul_f32 v[170:171], v[138:139], v[40:41] op_sel_hi:[1,0]
	v_pk_mul_f32 v[168:169], v[8:9], v[168:169]
	v_pk_mul_f32 v[170:171], v[10:11], v[170:171]
	global_store_dwordx4 v[184:185], v[168:171], off offset:1024
	v_pk_mul_f32 v[172:173], v[140:141], v[40:41] op_sel_hi:[1,0]
	v_pk_mul_f32 v[174:175], v[142:143], v[40:41] op_sel_hi:[1,0]
	v_pk_mul_f32 v[172:173], v[16:17], v[172:173]
	v_pk_mul_f32 v[174:175], v[18:19], v[174:175]
	global_store_dwordx4 v[184:185], v[172:175], off offset:2048
	v_pk_mul_f32 v[176:177], v[144:145], v[40:41] op_sel_hi:[1,0]
	v_pk_mul_f32 v[178:179], v[146:147], v[40:41] op_sel_hi:[1,0]
	v_pk_mul_f32 v[176:177], v[28:29], v[176:177]
	v_pk_mul_f32 v[178:179], v[30:31], v[178:179]
	global_store_dwordx4 v[184:185], v[176:179], off offset:3072
	v_lshl_add_u64 v[184:185], v[36:37], 0, v[96:97]
	global_load_dwordx4 v[132:135], v[184:185], off
	global_load_dwordx4 v[136:139], v[184:185], off offset:1024
	global_load_dwordx4 v[140:143], v[184:185], off offset:2048
	global_load_dwordx4 v[144:147], v[184:185], off offset:3072
	v_lshl_add_u64 v[36:37], v[36:37], 0, s[60:61]
	s_waitcnt vmcnt(24)
	v_pk_mul_f32 v[40:41], v[150:151], v[150:151]
	v_pk_mul_f32 v[42:43], v[148:149], v[148:149]
	v_mul_f32_e32 v33, v160, v160
	v_pk_mov_b32 v[44:45], v[42:43], v[40:41] op_sel:[1,0]
	v_mov_b32_e32 v43, v41
	v_pk_add_f32 v[40:41], v[44:45], v[42:43]
	v_pk_mul_f32 v[42:43], v[154:155], v[154:155]
	v_pk_mul_f32 v[44:45], v[152:153], v[152:153]
	v_pk_add_f32 v[40:41], v[40:41], v[40:41] op_sel:[0,1] op_sel_hi:[1,0]
	v_pk_mov_b32 v[46:47], v[44:45], v[42:43] op_sel:[1,0]
	v_mov_b32_e32 v45, v43
	v_pk_add_f32 v[42:43], v[46:47], v[44:45]
	v_mul_f32_e32 v44, v161, v161
	v_pk_add_f32 v[42:43], v[42:43], v[42:43] op_sel:[0,1] op_sel_hi:[1,0]
	v_mov_b32_e32 v41, v33
	v_mov_b32_e32 v43, v44
	v_pk_add_f32 v[40:41], v[40:41], v[42:43]
	v_mul_f32_e32 v42, v157, v157
	v_mul_f32_e32 v45, v162, v162
	v_pk_fma_f32 v[42:43], v[156:157], v[156:157], v[42:43] op_sel_hi:[1,1,0]
	v_mul_f32_e32 v44, v159, v159
	v_mul_f32_e32 v46, v163, v163
	v_mov_b32_e32 v43, v45
	v_pk_fma_f32 v[44:45], v[158:159], v[158:159], v[44:45] op_sel_hi:[1,1,0]
	s_nop 0
	v_mov_b32_e32 v45, v46
	v_pk_add_f32 v[42:43], v[42:43], v[44:45]
	s_nop 0
	v_pk_add_f32 v[40:41], v[40:41], v[42:43]
	s_nop 0
	v_add_f32_e32 v33, v40, v41
	v_and_b32_e32 v40, 64, v236
	v_add_u32_e32 v40, 64, v40
	v_xor_b32_e32 v41, 1, v236
	v_cmp_lt_i32_e32 vcc, v41, v40
	s_nop 1
	v_cndmask_b32_e32 v41, v236, v41, vcc
	v_lshlrev_b32_e32 v41, 2, v41
	ds_bpermute_b32 v41, v41, v33
	s_waitcnt lgkmcnt(0)
	v_add_f32_e32 v33, v33, v41
	v_xor_b32_e32 v41, 2, v236
	v_cmp_lt_i32_e32 vcc, v41, v40
	s_nop 1
	v_cndmask_b32_e32 v41, v236, v41, vcc
	v_lshlrev_b32_e32 v41, 2, v41
	ds_bpermute_b32 v41, v41, v33
	s_waitcnt lgkmcnt(0)
	v_add_f32_e32 v33, v33, v41
	v_xor_b32_e32 v41, 4, v236
	v_cmp_lt_i32_e32 vcc, v41, v40
	s_nop 1
	v_cndmask_b32_e32 v41, v236, v41, vcc
	v_lshlrev_b32_e32 v41, 2, v41
	ds_bpermute_b32 v41, v41, v33
	s_waitcnt lgkmcnt(0)
	v_add_f32_e32 v33, v33, v41
	v_xor_b32_e32 v41, 8, v236
	v_cmp_lt_i32_e32 vcc, v41, v40
	s_nop 1
	v_cndmask_b32_e32 v41, v236, v41, vcc
	v_lshlrev_b32_e32 v41, 2, v41
	ds_bpermute_b32 v41, v41, v33
	s_waitcnt lgkmcnt(0)
	v_add_f32_e32 v33, v33, v41
	v_xor_b32_e32 v41, 16, v236
	v_cmp_lt_i32_e32 vcc, v41, v40
	s_nop 1
	v_cndmask_b32_e32 v41, v236, v41, vcc
	v_lshlrev_b32_e32 v41, 2, v41
	ds_bpermute_b32 v41, v41, v33
	s_waitcnt lgkmcnt(0)
	v_add_f32_e32 v33, v33, v41
	v_xor_b32_e32 v41, 32, v236
	v_cmp_lt_i32_e32 vcc, v41, v40
	s_nop 1
	v_cndmask_b32_e32 v40, v236, v41, vcc
	v_lshlrev_b32_e32 v40, 2, v40
	ds_bpermute_b32 v40, v40, v33
	s_waitcnt lgkmcnt(0)
; __device__ __forceinline__ int otid() { int t = threadIdx.x; asm volatile("" : "+v"(t)); return t; }
; #define GAS __attribute__((address_space(1)))
; __device__ __forceinline__ float wave_sum(float v) {
; #pragma unroll
;     for (int o = 1; o < 64; o <<= 1) v += __shfl_xor(v, o);
;     return v;
; }
; __device__ void phase_final(const Params& p) {
;     const int tid = otid(), lane = tid & 63, gw = blockIdx.x * 8 + (tid >> 6), nw = gridDim.x * 8;
;     GAS const f32x4* gf = (GAS const f32x4*)(unsigned long long)p.norm_final;
;     for (int row = gw; row < NL; row += nw) {
;         GAS f32x4* xr = (GAS f32x4*)(unsigned long long)(p.out + (size_t)row * DM);
;         f32x4 v[4], g4[4];
; #pragma unroll
;         for (int j = 0; j < 4; ++j) { v[j] = xr[lane + 64 * j]; g4[j] = gf[lane + 64 * j]; }
;         asm volatile("" ::: "memory");
;         float s = 0.f;
; #pragma unroll
;         for (int j = 0; j < 4; ++j) s += (v[j].x * v[j].x + v[j].y * v[j].y) + (v[j].z * v[j].z + v[j].w * v[j].w);
;         const float rstd = rsqrtf(wave_sum(s) * (1.f / 1024.f) + 1e-6f);
; #pragma unroll
;         for (int j = 0; j < 4; ++j) xr[lane + 64 * j] = v[j] * rstd * g4[j];
;     }
; }
	v_add_f32_e32 v33, v33, v40
	v_fmamk_f32 v33, v33, 0x3a800000, v233
	v_cmp_gt_f32_e32 vcc, s58, v33
	v_mul_f32_e32 v40, 0x4b800000, v33
	s_nop 0
	v_cndmask_b32_e32 v33, v33, v40, vcc
	v_rsq_f32_e32 v33, v33
	s_nop 0
	v_mul_f32_e32 v40, 0x45800000, v33
	v_cndmask_b32_e32 v40, v33, v40, vcc
	v_pk_mul_f32 v[164:165], v[148:149], v[40:41] op_sel_hi:[1,0]
	v_pk_mul_f32 v[166:167], v[150:151], v[40:41] op_sel_hi:[1,0]
	v_pk_mul_f32 v[164:165], v[0:1], v[164:165]
	v_pk_mul_f32 v[166:167], v[2:3], v[166:167]
	global_store_dwordx4 v[186:187], v[164:167], off
	v_pk_mul_f32 v[168:169], v[152:153], v[40:41] op_sel_hi:[1,0]
	v_pk_mul_f32 v[170:171], v[154:155], v[40:41] op_sel_hi:[1,0]
	v_pk_mul_f32 v[168:169], v[8:9], v[168:169]
	v_pk_mul_f32 v[170:171], v[10:11], v[170:171]
	global_store_dwordx4 v[186:187], v[168:171], off offset:1024
	v_pk_mul_f32 v[172:173], v[156:157], v[40:41] op_sel_hi:[1,0]
	v_pk_mul_f32 v[174:175], v[158:159], v[40:41] op_sel_hi:[1,0]
	v_pk_mul_f32 v[172:173], v[16:17], v[172:173]
	v_pk_mul_f32 v[174:175], v[18:19], v[174:175]
	global_store_dwordx4 v[186:187], v[172:175], off offset:2048
	v_pk_mul_f32 v[176:177], v[160:161], v[40:41] op_sel_hi:[1,0]
	v_pk_mul_f32 v[178:179], v[162:163], v[40:41] op_sel_hi:[1,0]
	v_pk_mul_f32 v[176:177], v[28:29], v[176:177]
	v_pk_mul_f32 v[178:179], v[30:31], v[178:179]
	global_store_dwordx4 v[186:187], v[176:179], off offset:3072
	v_lshl_add_u64 v[186:187], v[36:37], 0, v[96:97]
	global_load_dwordx4 v[148:151], v[186:187], off
	global_load_dwordx4 v[152:155], v[186:187], off offset:1024
	global_load_dwordx4 v[156:159], v[186:187], off offset:2048
	global_load_dwordx4 v[160:163], v[186:187], off offset:3072
	v_lshl_add_u64 v[36:37], v[36:37], 0, s[60:61]
	s_waitcnt vmcnt(24)
	v_pk_mul_f32 v[40:41], v[102:103], v[102:103]
	v_pk_mul_f32 v[42:43], v[100:101], v[100:101]
	v_mul_f32_e32 v33, v112, v112
	v_pk_mov_b32 v[44:45], v[42:43], v[40:41] op_sel:[1,0]
	v_mov_b32_e32 v43, v41
	v_pk_add_f32 v[40:41], v[44:45], v[42:43]
	v_pk_mul_f32 v[42:43], v[106:107], v[106:107]
	v_pk_mul_f32 v[44:45], v[104:105], v[104:105]
	v_pk_add_f32 v[40:41], v[40:41], v[40:41] op_sel:[0,1] op_sel_hi:[1,0]
	v_pk_mov_b32 v[46:47], v[44:45], v[42:43] op_sel:[1,0]
	v_mov_b32_e32 v45, v43
	v_pk_add_f32 v[42:43], v[46:47], v[44:45]
	v_mul_f32_e32 v44, v113, v113
	v_pk_add_f32 v[42:43], v[42:43], v[42:43] op_sel:[0,1] op_sel_hi:[1,0]
	v_mov_b32_e32 v41, v33
	v_mov_b32_e32 v43, v44
	v_pk_add_f32 v[40:41], v[40:41], v[42:43]
	v_mul_f32_e32 v42, v109, v109
	v_mul_f32_e32 v45, v114, v114
	v_pk_fma_f32 v[42:43], v[108:109], v[108:109], v[42:43] op_sel_hi:[1,1,0]
	v_mul_f32_e32 v44, v111, v111
	v_mul_f32_e32 v46, v115, v115
	v_mov_b32_e32 v43, v45
	v_pk_fma_f32 v[44:45], v[110:111], v[110:111], v[44:45] op_sel_hi:[1,1,0]
	s_nop 0
	v_mov_b32_e32 v45, v46
	v_pk_add_f32 v[42:43], v[42:43], v[44:45]
	s_nop 0
	v_pk_add_f32 v[40:41], v[40:41], v[42:43]
	s_nop 0
	v_add_f32_e32 v33, v40, v41
	v_and_b32_e32 v40, 64, v236
	v_add_u32_e32 v40, 64, v40
	v_xor_b32_e32 v41, 1, v236
	v_cmp_lt_i32_e32 vcc, v41, v40
	s_nop 1
	v_cndmask_b32_e32 v41, v236, v41, vcc
	v_lshlrev_b32_e32 v41, 2, v41
	ds_bpermute_b32 v41, v41, v33
	s_waitcnt lgkmcnt(0)
	v_add_f32_e32 v33, v33, v41
	v_xor_b32_e32 v41, 2, v236
	v_cmp_lt_i32_e32 vcc, v41, v40
	s_nop 1
	v_cndmask_b32_e32 v41, v236, v41, vcc
	v_lshlrev_b32_e32 v41, 2, v41
	ds_bpermute_b32 v41, v41, v33
	s_waitcnt lgkmcnt(0)
	v_add_f32_e32 v33, v33, v41
	v_xor_b32_e32 v41, 4, v236
	v_cmp_lt_i32_e32 vcc, v41, v40
	s_nop 1
	v_cndmask_b32_e32 v41, v236, v41, vcc
	v_lshlrev_b32_e32 v41, 2, v41
	ds_bpermute_b32 v41, v41, v33
	s_waitcnt lgkmcnt(0)
	v_add_f32_e32 v33, v33, v41
	v_xor_b32_e32 v41, 8, v236
	v_cmp_lt_i32_e32 vcc, v41, v40
	s_nop 1
	v_cndmask_b32_e32 v41, v236, v41, vcc
	v_lshlrev_b32_e32 v41, 2, v41
	ds_bpermute_b32 v41, v41, v33
	s_waitcnt lgkmcnt(0)
	v_add_f32_e32 v33, v33, v41
	v_xor_b32_e32 v41, 16, v236
	v_cmp_lt_i32_e32 vcc, v41, v40
	s_nop 1
	v_cndmask_b32_e32 v41, v236, v41, vcc
	v_lshlrev_b32_e32 v41, 2, v41
	ds_bpermute_b32 v41, v41, v33
	s_waitcnt lgkmcnt(0)
	v_add_f32_e32 v33, v33, v41
	v_xor_b32_e32 v41, 32, v236
	v_cmp_lt_i32_e32 vcc, v41, v40
	s_nop 1
	v_cndmask_b32_e32 v40, v236, v41, vcc
	v_lshlrev_b32_e32 v40, 2, v40
	ds_bpermute_b32 v40, v40, v33
	s_waitcnt lgkmcnt(0)
	v_add_f32_e32 v33, v33, v40
	v_fmamk_f32 v33, v33, 0x3a800000, v233
	v_cmp_gt_f32_e32 vcc, s58, v33
	v_mul_f32_e32 v40, 0x4b800000, v33
	s_nop 0
	v_cndmask_b32_e32 v33, v33, v40, vcc
	v_rsq_f32_e32 v33, v33
	s_nop 0
	v_mul_f32_e32 v40, 0x45800000, v33
	v_cndmask_b32_e32 v40, v33, v40, vcc
	v_pk_mul_f32 v[164:165], v[100:101], v[40:41] op_sel_hi:[1,0]
	v_pk_mul_f32 v[166:167], v[102:103], v[40:41] op_sel_hi:[1,0]
	v_pk_mul_f32 v[164:165], v[0:1], v[164:165]
	v_pk_mul_f32 v[166:167], v[2:3], v[166:167]
	global_store_dwordx4 v[180:181], v[164:167], off
	v_pk_mul_f32 v[168:169], v[104:105], v[40:41] op_sel_hi:[1,0]
	v_pk_mul_f32 v[170:171], v[106:107], v[40:41] op_sel_hi:[1,0]
	v_pk_mul_f32 v[168:169], v[8:9], v[168:169]
	v_pk_mul_f32 v[170:171], v[10:11], v[170:171]
	global_store_dwordx4 v[180:181], v[168:171], off offset:1024
	v_pk_mul_f32 v[172:173], v[108:109], v[40:41] op_sel_hi:[1,0]
	v_pk_mul_f32 v[174:175], v[110:111], v[40:41] op_sel_hi:[1,0]
	v_pk_mul_f32 v[172:173], v[16:17], v[172:173]
	v_pk_mul_f32 v[174:175], v[18:19], v[174:175]
	global_store_dwordx4 v[180:181], v[172:175], off offset:2048
	v_pk_mul_f32 v[176:177], v[112:113], v[40:41] op_sel_hi:[1,0]
	v_pk_mul_f32 v[178:179], v[114:115], v[40:41] op_sel_hi:[1,0]
	v_pk_mul_f32 v[176:177], v[28:29], v[176:177]
	v_pk_mul_f32 v[178:179], v[30:31], v[178:179]
	global_store_dwordx4 v[180:181], v[176:179], off offset:3072
	s_waitcnt vmcnt(20)
; __device__ __forceinline__ int otid() { int t = threadIdx.x; asm volatile("" : "+v"(t)); return t; }
; #define GAS __attribute__((address_space(1)))
; __device__ __forceinline__ float wave_sum(float v) {
; #pragma unroll
;     for (int o = 1; o < 64; o <<= 1) v += __shfl_xor(v, o);
;     return v;
; }
; __device__ void phase_final(const Params& p) {
;     const int tid = otid(), lane = tid & 63, gw = blockIdx.x * 8 + (tid >> 6), nw = gridDim.x * 8;
;     GAS const f32x4* gf = (GAS const f32x4*)(unsigned long long)p.norm_final;
;     for (int row = gw; row < NL; row += nw) {
;         GAS f32x4* xr = (GAS f32x4*)(unsigned long long)(p.out + (size_t)row * DM);
;         f32x4 v[4], g4[4];
; #pragma unroll
;         for (int j = 0; j < 4; ++j) { v[j] = xr[lane + 64 * j]; g4[j] = gf[lane + 64 * j]; }
;         asm volatile("" ::: "memory");
;         float s = 0.f;
; #pragma unroll
;         for (int j = 0; j < 4; ++j) s += (v[j].x * v[j].x + v[j].y * v[j].y) + (v[j].z * v[j].z + v[j].w * v[j].w);
;         const float rstd = rsqrtf(wave_sum(s) * (1.f / 1024.f) + 1e-6f);
; #pragma unroll
;         for (int j = 0; j < 4; ++j) xr[lane + 64 * j] = v[j] * rstd * g4[j];
;     }
; }
	v_pk_mul_f32 v[40:41], v[118:119], v[118:119]
	v_pk_mul_f32 v[42:43], v[116:117], v[116:117]
	v_mul_f32_e32 v33, v128, v128
	v_pk_mov_b32 v[44:45], v[42:43], v[40:41] op_sel:[1,0]
	v_mov_b32_e32 v43, v41
	v_pk_add_f32 v[40:41], v[44:45], v[42:43]
	v_pk_mul_f32 v[42:43], v[122:123], v[122:123]
	v_pk_mul_f32 v[44:45], v[120:121], v[120:121]
	v_pk_add_f32 v[40:41], v[40:41], v[40:41] op_sel:[0,1] op_sel_hi:[1,0]
	v_pk_mov_b32 v[46:47], v[44:45], v[42:43] op_sel:[1,0]
	v_mov_b32_e32 v45, v43
	v_pk_add_f32 v[42:43], v[46:47], v[44:45]
	v_mul_f32_e32 v44, v129, v129
	v_pk_add_f32 v[42:43], v[42:43], v[42:43] op_sel:[0,1] op_sel_hi:[1,0]
	v_mov_b32_e32 v41, v33
	v_mov_b32_e32 v43, v44
	v_pk_add_f32 v[40:41], v[40:41], v[42:43]
	v_mul_f32_e32 v42, v125, v125
	v_mul_f32_e32 v45, v130, v130
	v_pk_fma_f32 v[42:43], v[124:125], v[124:125], v[42:43] op_sel_hi:[1,1,0]
	v_mul_f32_e32 v44, v127, v127
	v_mul_f32_e32 v46, v131, v131
	v_mov_b32_e32 v43, v45
	v_pk_fma_f32 v[44:45], v[126:127], v[126:127], v[44:45] op_sel_hi:[1,1,0]
	s_nop 0
	v_mov_b32_e32 v45, v46
	v_pk_add_f32 v[42:43], v[42:43], v[44:45]
	s_nop 0
	v_pk_add_f32 v[40:41], v[40:41], v[42:43]
	s_nop 0
	v_add_f32_e32 v33, v40, v41
	v_and_b32_e32 v40, 64, v236
	v_add_u32_e32 v40, 64, v40
	v_xor_b32_e32 v41, 1, v236
	v_cmp_lt_i32_e32 vcc, v41, v40
	s_nop 1
	v_cndmask_b32_e32 v41, v236, v41, vcc
	v_lshlrev_b32_e32 v41, 2, v41
	ds_bpermute_b32 v41, v41, v33
	s_waitcnt lgkmcnt(0)
	v_add_f32_e32 v33, v33, v41
	v_xor_b32_e32 v41, 2, v236
	v_cmp_lt_i32_e32 vcc, v41, v40
	s_nop 1
	v_cndmask_b32_e32 v41, v236, v41, vcc
	v_lshlrev_b32_e32 v41, 2, v41
	ds_bpermute_b32 v41, v41, v33
	s_waitcnt lgkmcnt(0)
	v_add_f32_e32 v33, v33, v41
	v_xor_b32_e32 v41, 4, v236
	v_cmp_lt_i32_e32 vcc, v41, v40
	s_nop 1
	v_cndmask_b32_e32 v41, v236, v41, vcc
	v_lshlrev_b32_e32 v41, 2, v41
	ds_bpermute_b32 v41, v41, v33
	s_waitcnt lgkmcnt(0)
	v_add_f32_e32 v33, v33, v41
	v_xor_b32_e32 v41, 8, v236
	v_cmp_lt_i32_e32 vcc, v41, v40
	s_nop 1
	v_cndmask_b32_e32 v41, v236, v41, vcc
	v_lshlrev_b32_e32 v41, 2, v41
	ds_bpermute_b32 v41, v41, v33
	s_waitcnt lgkmcnt(0)
	v_add_f32_e32 v33, v33, v41
	v_xor_b32_e32 v41, 16, v236
	v_cmp_lt_i32_e32 vcc, v41, v40
	s_nop 1
	v_cndmask_b32_e32 v41, v236, v41, vcc
	v_lshlrev_b32_e32 v41, 2, v41
	ds_bpermute_b32 v41, v41, v33
	s_waitcnt lgkmcnt(0)
	v_add_f32_e32 v33, v33, v41
	v_xor_b32_e32 v41, 32, v236
	v_cmp_lt_i32_e32 vcc, v41, v40
	s_nop 1
	v_cndmask_b32_e32 v40, v236, v41, vcc
	v_lshlrev_b32_e32 v40, 2, v40
	ds_bpermute_b32 v40, v40, v33
	s_waitcnt lgkmcnt(0)
	v_add_f32_e32 v33, v33, v40
	v_fmamk_f32 v33, v33, 0x3a800000, v233
	v_cmp_gt_f32_e32 vcc, s58, v33
	v_mul_f32_e32 v40, 0x4b800000, v33
	s_nop 0
	v_cndmask_b32_e32 v33, v33, v40, vcc
	v_rsq_f32_e32 v33, v33
	s_nop 0
	v_mul_f32_e32 v40, 0x45800000, v33
	v_cndmask_b32_e32 v40, v33, v40, vcc
	v_pk_mul_f32 v[164:165], v[116:117], v[40:41] op_sel_hi:[1,0]
	v_pk_mul_f32 v[166:167], v[118:119], v[40:41] op_sel_hi:[1,0]
	v_pk_mul_f32 v[164:165], v[0:1], v[164:165]
	v_pk_mul_f32 v[166:167], v[2:3], v[166:167]
	global_store_dwordx4 v[182:183], v[164:167], off
	v_pk_mul_f32 v[168:169], v[120:121], v[40:41] op_sel_hi:[1,0]
	v_pk_mul_f32 v[170:171], v[122:123], v[40:41] op_sel_hi:[1,0]
	v_pk_mul_f32 v[168:169], v[8:9], v[168:169]
	v_pk_mul_f32 v[170:171], v[10:11], v[170:171]
	global_store_dwordx4 v[182:183], v[168:171], off offset:1024
	v_pk_mul_f32 v[172:173], v[124:125], v[40:41] op_sel_hi:[1,0]
	v_pk_mul_f32 v[174:175], v[126:127], v[40:41] op_sel_hi:[1,0]
	v_pk_mul_f32 v[172:173], v[16:17], v[172:173]
	v_pk_mul_f32 v[174:175], v[18:19], v[174:175]
	global_store_dwordx4 v[182:183], v[172:175], off offset:2048
	v_pk_mul_f32 v[176:177], v[128:129], v[40:41] op_sel_hi:[1,0]
	v_pk_mul_f32 v[178:179], v[130:131], v[40:41] op_sel_hi:[1,0]
	v_pk_mul_f32 v[176:177], v[28:29], v[176:177]
	v_pk_mul_f32 v[178:179], v[30:31], v[178:179]
	global_store_dwordx4 v[182:183], v[176:179], off offset:3072
	s_waitcnt vmcnt(16)
	v_pk_mul_f32 v[40:41], v[134:135], v[134:135]
	v_pk_mul_f32 v[42:43], v[132:133], v[132:133]
	v_mul_f32_e32 v33, v144, v144
	v_pk_mov_b32 v[44:45], v[42:43], v[40:41] op_sel:[1,0]
	v_mov_b32_e32 v43, v41
	v_pk_add_f32 v[40:41], v[44:45], v[42:43]
	v_pk_mul_f32 v[42:43], v[138:139], v[138:139]
	v_pk_mul_f32 v[44:45], v[136:137], v[136:137]
	v_pk_add_f32 v[40:41], v[40:41], v[40:41] op_sel:[0,1] op_sel_hi:[1,0]
	v_pk_mov_b32 v[46:47], v[44:45], v[42:43] op_sel:[1,0]
	v_mov_b32_e32 v45, v43
	v_pk_add_f32 v[42:43], v[46:47], v[44:45]
	v_mul_f32_e32 v44, v145, v145
	v_pk_add_f32 v[42:43], v[42:43], v[42:43] op_sel:[0,1] op_sel_hi:[1,0]
	v_mov_b32_e32 v41, v33
	v_mov_b32_e32 v43, v44
	v_pk_add_f32 v[40:41], v[40:41], v[42:43]
	v_mul_f32_e32 v42, v141, v141
	v_mul_f32_e32 v45, v146, v146
	v_pk_fma_f32 v[42:43], v[140:141], v[140:141], v[42:43] op_sel_hi:[1,1,0]
	v_mul_f32_e32 v44, v143, v143
	v_mul_f32_e32 v46, v147, v147
	v_mov_b32_e32 v43, v45
	v_pk_fma_f32 v[44:45], v[142:143], v[142:143], v[44:45] op_sel_hi:[1,1,0]
	s_nop 0
	v_mov_b32_e32 v45, v46
	v_pk_add_f32 v[42:43], v[42:43], v[44:45]
	s_nop 0
	v_pk_add_f32 v[40:41], v[40:41], v[42:43]
	s_nop 0
	v_add_f32_e32 v33, v40, v41
	v_and_b32_e32 v40, 64, v236
	v_add_u32_e32 v40, 64, v40
	v_xor_b32_e32 v41, 1, v236
	v_cmp_lt_i32_e32 vcc, v41, v40
	s_nop 1
	v_cndmask_b32_e32 v41, v236, v41, vcc
	v_lshlrev_b32_e32 v41, 2, v41
	ds_bpermute_b32 v41, v41, v33
	s_waitcnt lgkmcnt(0)
	v_add_f32_e32 v33, v33, v41
	v_xor_b32_e32 v41, 2, v236
	v_cmp_lt_i32_e32 vcc, v41, v40
	s_nop 1
	v_cndmask_b32_e32 v41, v236, v41, vcc
	v_lshlrev_b32_e32 v41, 2, v41
	ds_bpermute_b32 v41, v41, v33
	s_waitcnt lgkmcnt(0)
; __device__ __forceinline__ int otid() { int t = threadIdx.x; asm volatile("" : "+v"(t)); return t; }
; #define GAS __attribute__((address_space(1)))
; __device__ __forceinline__ float wave_sum(float v) {
; #pragma unroll
;     for (int o = 1; o < 64; o <<= 1) v += __shfl_xor(v, o);
;     return v;
; }
; __device__ void phase_final(const Params& p) {
;     const int tid = otid(), lane = tid & 63, gw = blockIdx.x * 8 + (tid >> 6), nw = gridDim.x * 8;
;     GAS const f32x4* gf = (GAS const f32x4*)(unsigned long long)p.norm_final;
;     for (int row = gw; row < NL; row += nw) {
;         GAS f32x4* xr = (GAS f32x4*)(unsigned long long)(p.out + (size_t)row * DM);
;         f32x4 v[4], g4[4];
; #pragma unroll
;         for (int j = 0; j < 4; ++j) { v[j] = xr[lane + 64 * j]; g4[j] = gf[lane + 64 * j]; }
;         asm volatile("" ::: "memory");
;         float s = 0.f;
; #pragma unroll
;         for (int j = 0; j < 4; ++j) s += (v[j].x * v[j].x + v[j].y * v[j].y) + (v[j].z * v[j].z + v[j].w * v[j].w);
;         const float rstd = rsqrtf(wave_sum(s) * (1.f / 1024.f) + 1e-6f);
; #pragma unroll
;         for (int j = 0; j < 4; ++j) xr[lane + 64 * j] = v[j] * rstd * g4[j];
;     }
; }
	v_add_f32_e32 v33, v33, v41
	v_xor_b32_e32 v41, 4, v236
	v_cmp_lt_i32_e32 vcc, v41, v40
	s_nop 1
	v_cndmask_b32_e32 v41, v236, v41, vcc
	v_lshlrev_b32_e32 v41, 2, v41
	ds_bpermute_b32 v41, v41, v33
	s_waitcnt lgkmcnt(0)
	v_add_f32_e32 v33, v33, v41
	v_xor_b32_e32 v41, 8, v236
	v_cmp_lt_i32_e32 vcc, v41, v40
	s_nop 1
	v_cndmask_b32_e32 v41, v236, v41, vcc
	v_lshlrev_b32_e32 v41, 2, v41
	ds_bpermute_b32 v41, v41, v33
	s_waitcnt lgkmcnt(0)
	v_add_f32_e32 v33, v33, v41
	v_xor_b32_e32 v41, 16, v236
	v_cmp_lt_i32_e32 vcc, v41, v40
	s_nop 1
	v_cndmask_b32_e32 v41, v236, v41, vcc
	v_lshlrev_b32_e32 v41, 2, v41
	ds_bpermute_b32 v41, v41, v33
	s_waitcnt lgkmcnt(0)
	v_add_f32_e32 v33, v33, v41
	v_xor_b32_e32 v41, 32, v236
	v_cmp_lt_i32_e32 vcc, v41, v40
	s_nop 1
	v_cndmask_b32_e32 v40, v236, v41, vcc
	v_lshlrev_b32_e32 v40, 2, v40
	ds_bpermute_b32 v40, v40, v33
	s_waitcnt lgkmcnt(0)
	v_add_f32_e32 v33, v33, v40
	v_fmamk_f32 v33, v33, 0x3a800000, v233
	v_cmp_gt_f32_e32 vcc, s58, v33
	v_mul_f32_e32 v40, 0x4b800000, v33
	s_nop 0
	v_cndmask_b32_e32 v33, v33, v40, vcc
	v_rsq_f32_e32 v33, v33
	s_nop 0
	v_mul_f32_e32 v40, 0x45800000, v33
	v_cndmask_b32_e32 v40, v33, v40, vcc
	v_pk_mul_f32 v[164:165], v[132:133], v[40:41] op_sel_hi:[1,0]
	v_pk_mul_f32 v[166:167], v[134:135], v[40:41] op_sel_hi:[1,0]
	v_pk_mul_f32 v[164:165], v[0:1], v[164:165]
	v_pk_mul_f32 v[166:167], v[2:3], v[166:167]
	global_store_dwordx4 v[184:185], v[164:167], off
	v_pk_mul_f32 v[168:169], v[136:137], v[40:41] op_sel_hi:[1,0]
	v_pk_mul_f32 v[170:171], v[138:139], v[40:41] op_sel_hi:[1,0]
	v_pk_mul_f32 v[168:169], v[8:9], v[168:169]
	v_pk_mul_f32 v[170:171], v[10:11], v[170:171]
	global_store_dwordx4 v[184:185], v[168:171], off offset:1024
	v_pk_mul_f32 v[172:173], v[140:141], v[40:41] op_sel_hi:[1,0]
	v_pk_mul_f32 v[174:175], v[142:143], v[40:41] op_sel_hi:[1,0]
	v_pk_mul_f32 v[172:173], v[16:17], v[172:173]
	v_pk_mul_f32 v[174:175], v[18:19], v[174:175]
	global_store_dwordx4 v[184:185], v[172:175], off offset:2048
	v_pk_mul_f32 v[176:177], v[144:145], v[40:41] op_sel_hi:[1,0]
	v_pk_mul_f32 v[178:179], v[146:147], v[40:41] op_sel_hi:[1,0]
	v_pk_mul_f32 v[176:177], v[28:29], v[176:177]
	v_pk_mul_f32 v[178:179], v[30:31], v[178:179]
	global_store_dwordx4 v[184:185], v[176:179], off offset:3072
	s_waitcnt vmcnt(12)
	v_pk_mul_f32 v[40:41], v[150:151], v[150:151]
	v_pk_mul_f32 v[42:43], v[148:149], v[148:149]
	v_mul_f32_e32 v33, v160, v160
	v_pk_mov_b32 v[44:45], v[42:43], v[40:41] op_sel:[1,0]
	v_mov_b32_e32 v43, v41
	v_pk_add_f32 v[40:41], v[44:45], v[42:43]
	v_pk_mul_f32 v[42:43], v[154:155], v[154:155]
	v_pk_mul_f32 v[44:45], v[152:153], v[152:153]
	v_pk_add_f32 v[40:41], v[40:41], v[40:41] op_sel:[0,1] op_sel_hi:[1,0]
	v_pk_mov_b32 v[46:47], v[44:45], v[42:43] op_sel:[1,0]
	v_mov_b32_e32 v45, v43
	v_pk_add_f32 v[42:43], v[46:47], v[44:45]
	v_mul_f32_e32 v44, v161, v161
	v_pk_add_f32 v[42:43], v[42:43], v[42:43] op_sel:[0,1] op_sel_hi:[1,0]
	v_mov_b32_e32 v41, v33
	v_mov_b32_e32 v43, v44
	v_pk_add_f32 v[40:41], v[40:41], v[42:43]
	v_mul_f32_e32 v42, v157, v157
	v_mul_f32_e32 v45, v162, v162
	v_pk_fma_f32 v[42:43], v[156:157], v[156:157], v[42:43] op_sel_hi:[1,1,0]
	v_mul_f32_e32 v44, v159, v159
	v_mul_f32_e32 v46, v163, v163
	v_mov_b32_e32 v43, v45
	v_pk_fma_f32 v[44:45], v[158:159], v[158:159], v[44:45] op_sel_hi:[1,1,0]
	s_nop 0
	v_mov_b32_e32 v45, v46
	v_pk_add_f32 v[42:43], v[42:43], v[44:45]
	s_nop 0
	v_pk_add_f32 v[40:41], v[40:41], v[42:43]
	s_nop 0
	v_add_f32_e32 v33, v40, v41
	v_and_b32_e32 v40, 64, v236
	v_add_u32_e32 v40, 64, v40
	v_xor_b32_e32 v41, 1, v236
	v_cmp_lt_i32_e32 vcc, v41, v40
	s_nop 1
	v_cndmask_b32_e32 v41, v236, v41, vcc
	v_lshlrev_b32_e32 v41, 2, v41
	ds_bpermute_b32 v41, v41, v33
	s_waitcnt lgkmcnt(0)
	v_add_f32_e32 v33, v33, v41
	v_xor_b32_e32 v41, 2, v236
	v_cmp_lt_i32_e32 vcc, v41, v40
	s_nop 1
	v_cndmask_b32_e32 v41, v236, v41, vcc
	v_lshlrev_b32_e32 v41, 2, v41
	ds_bpermute_b32 v41, v41, v33
	s_waitcnt lgkmcnt(0)
	v_add_f32_e32 v33, v33, v41
	v_xor_b32_e32 v41, 4, v236
	v_cmp_lt_i32_e32 vcc, v41, v40
	s_nop 1
	v_cndmask_b32_e32 v41, v236, v41, vcc
	v_lshlrev_b32_e32 v41, 2, v41
	ds_bpermute_b32 v41, v41, v33
	s_waitcnt lgkmcnt(0)
	v_add_f32_e32 v33, v33, v41
	v_xor_b32_e32 v41, 8, v236
	v_cmp_lt_i32_e32 vcc, v41, v40
	s_nop 1
	v_cndmask_b32_e32 v41, v236, v41, vcc
	v_lshlrev_b32_e32 v41, 2, v41
	ds_bpermute_b32 v41, v41, v33
	s_waitcnt lgkmcnt(0)
	v_add_f32_e32 v33, v33, v41
	v_xor_b32_e32 v41, 16, v236
	v_cmp_lt_i32_e32 vcc, v41, v40
	s_nop 1
	v_cndmask_b32_e32 v41, v236, v41, vcc
	v_lshlrev_b32_e32 v41, 2, v41
	ds_bpermute_b32 v41, v41, v33
	s_waitcnt lgkmcnt(0)
	v_add_f32_e32 v33, v33, v41
	v_xor_b32_e32 v41, 32, v236
	v_cmp_lt_i32_e32 vcc, v41, v40
	s_nop 1
	v_cndmask_b32_e32 v40, v236, v41, vcc
	v_lshlrev_b32_e32 v40, 2, v40
	ds_bpermute_b32 v40, v40, v33
	s_waitcnt lgkmcnt(0)
	v_add_f32_e32 v33, v33, v40
	v_fmamk_f32 v33, v33, 0x3a800000, v233
	v_cmp_gt_f32_e32 vcc, s58, v33
	v_mul_f32_e32 v40, 0x4b800000, v33
	s_nop 0
	v_cndmask_b32_e32 v33, v33, v40, vcc
	v_rsq_f32_e32 v33, v33
	s_nop 0
	v_mul_f32_e32 v40, 0x45800000, v33
	v_cndmask_b32_e32 v40, v33, v40, vcc
	v_pk_mul_f32 v[164:165], v[148:149], v[40:41] op_sel_hi:[1,0]
	v_pk_mul_f32 v[166:167], v[150:151], v[40:41] op_sel_hi:[1,0]
	v_pk_mul_f32 v[164:165], v[0:1], v[164:165]
	v_pk_mul_f32 v[166:167], v[2:3], v[166:167]
	global_store_dwordx4 v[186:187], v[164:167], off
	v_pk_mul_f32 v[168:169], v[152:153], v[40:41] op_sel_hi:[1,0]
	v_pk_mul_f32 v[170:171], v[154:155], v[40:41] op_sel_hi:[1,0]
	v_pk_mul_f32 v[168:169], v[8:9], v[168:169]
	v_pk_mul_f32 v[170:171], v[10:11], v[170:171]
	global_store_dwordx4 v[186:187], v[168:171], off offset:1024
	v_pk_mul_f32 v[172:173], v[156:157], v[40:41] op_sel_hi:[1,0]
	v_pk_mul_f32 v[174:175], v[158:159], v[40:41] op_sel_hi:[1,0]
	v_pk_mul_f32 v[172:173], v[16:17], v[172:173]
	v_pk_mul_f32 v[174:175], v[18:19], v[174:175]
	global_store_dwordx4 v[186:187], v[172:175], off offset:2048
	v_pk_mul_f32 v[176:177], v[160:161], v[40:41] op_sel_hi:[1,0]
	v_pk_mul_f32 v[178:179], v[162:163], v[40:41] op_sel_hi:[1,0]
	v_pk_mul_f32 v[176:177], v[28:29], v[176:177]
	v_pk_mul_f32 v[178:179], v[30:31], v[178:179]
	global_store_dwordx4 v[186:187], v[176:179], off offset:3072
	s_branch .LBB0_648
; __device__ __forceinline__ int otid() { int t = threadIdx.x; asm volatile("" : "+v"(t)); return t; }
; #define GAS __attribute__((address_space(1)))
; __device__ void phase_final(const Params& p) {
;     const int tid = otid(), lane = tid & 63, gw = blockIdx.x * 8 + (tid >> 6), nw = gridDim.x * 8;
;     GAS const f32x4* gf = (GAS const f32x4*)(unsigned long long)p.norm_final;
;     for (int row = gw; row < NL; row += nw) {
;         GAS f32x4* xr = (GAS f32x4*)(unsigned long long)(p.out + (size_t)row * DM);
;         f32x4 v[4], g4[4];
; #pragma unroll
;         for (int j = 0; j < 4; ++j) { v[j] = xr[lane + 64 * j]; g4[j] = gf[lane + 64 * j]; }
;         asm volatile("" ::: "memory");
;         float s = 0.f;
; #pragma unroll
;         for (int j = 0; j < 4; ++j) s += (v[j].x * v[j].x + v[j].y * v[j].y) + (v[j].z * v[j].z + v[j].w * v[j].w);
;         const float rstd = rsqrtf(wave_sum(s) * (1.f / 1024.f) + 1e-6f);
; #pragma unroll
;         for (int j = 0; j < 4; ++j) xr[lane + 64 * j] = v[j] * rstd * g4[j];
;     }
; }
.Lmy_fn_generic:
.Lmy_fn_loop:
	v_lshl_add_u64 v[38:39], v[36:37], 0, v[96:97]
	global_load_dwordx4 v[4:7], v[38:39], off
	global_load_dwordx4 v[0:3], v[34:35], off
	global_load_dwordx4 v[12:15], v[38:39], off offset:1024
	global_load_dwordx4 v[8:11], v[34:35], off offset:1024
	global_load_dwordx4 v[20:23], v[38:39], off offset:2048
	global_load_dwordx4 v[16:19], v[34:35], off offset:2048
	global_load_dwordx4 v[24:27], v[38:39], off offset:3072
	global_load_dwordx4 v[28:31], v[34:35], off offset:3072
	v_add_u32_e32 v32, s74, v32
	v_lshl_add_u64 v[36:37], v[36:37], 0, s[60:61]
	s_waitcnt vmcnt(0)
	v_pk_mul_f32 v[40:41], v[6:7], v[6:7]
	v_pk_mul_f32 v[42:43], v[4:5], v[4:5]
	v_mul_f32_e32 v33, v24, v24
	v_pk_mov_b32 v[44:45], v[42:43], v[40:41] op_sel:[1,0]
	v_mov_b32_e32 v43, v41
	v_pk_add_f32 v[40:41], v[44:45], v[42:43]
	v_pk_mul_f32 v[42:43], v[14:15], v[14:15]
	v_pk_mul_f32 v[44:45], v[12:13], v[12:13]
	v_pk_add_f32 v[40:41], v[40:41], v[40:41] op_sel:[0,1] op_sel_hi:[1,0]
	v_pk_mov_b32 v[46:47], v[44:45], v[42:43] op_sel:[1,0]
	v_mov_b32_e32 v45, v43
	v_pk_add_f32 v[42:43], v[46:47], v[44:45]
	v_mul_f32_e32 v44, v25, v25
	v_pk_add_f32 v[42:43], v[42:43], v[42:43] op_sel:[0,1] op_sel_hi:[1,0]
	v_mov_b32_e32 v41, v33
	v_mov_b32_e32 v43, v44
	v_pk_add_f32 v[40:41], v[40:41], v[42:43]
	v_mul_f32_e32 v42, v21, v21
	v_mul_f32_e32 v45, v26, v26
	v_pk_fma_f32 v[42:43], v[20:21], v[20:21], v[42:43] op_sel_hi:[1,1,0]
	v_mul_f32_e32 v44, v23, v23
	v_mul_f32_e32 v46, v27, v27
	v_mov_b32_e32 v43, v45
	v_pk_fma_f32 v[44:45], v[22:23], v[22:23], v[44:45] op_sel_hi:[1,1,0]
	s_nop 0
	v_mov_b32_e32 v45, v46
	v_pk_add_f32 v[42:43], v[42:43], v[44:45]
	s_nop 0
	v_pk_add_f32 v[40:41], v[40:41], v[42:43]
	s_nop 0
	v_add_f32_e32 v33, v40, v41
	v_and_b32_e32 v40, 64, v236
	v_add_u32_e32 v40, 64, v40
	v_xor_b32_e32 v41, 1, v236
	v_cmp_lt_i32_e32 vcc, v41, v40
	s_nop 1
	v_cndmask_b32_e32 v41, v236, v41, vcc
	v_lshlrev_b32_e32 v41, 2, v41
	ds_bpermute_b32 v41, v41, v33
	s_waitcnt lgkmcnt(0)
	v_add_f32_e32 v33, v33, v41
	v_xor_b32_e32 v41, 2, v236
	v_cmp_lt_i32_e32 vcc, v41, v40
	s_nop 1
	v_cndmask_b32_e32 v41, v236, v41, vcc
	v_lshlrev_b32_e32 v41, 2, v41
	ds_bpermute_b32 v41, v41, v33
	s_waitcnt lgkmcnt(0)
	v_add_f32_e32 v33, v33, v41
	v_xor_b32_e32 v41, 4, v236
	v_cmp_lt_i32_e32 vcc, v41, v40
	s_nop 1
	v_cndmask_b32_e32 v41, v236, v41, vcc
	v_lshlrev_b32_e32 v41, 2, v41
	ds_bpermute_b32 v41, v41, v33
	s_waitcnt lgkmcnt(0)
	v_add_f32_e32 v33, v33, v41
	v_xor_b32_e32 v41, 8, v236
	v_cmp_lt_i32_e32 vcc, v41, v40
	s_nop 1
	v_cndmask_b32_e32 v41, v236, v41, vcc
	v_lshlrev_b32_e32 v41, 2, v41
	ds_bpermute_b32 v41, v41, v33
	s_waitcnt lgkmcnt(0)
	v_add_f32_e32 v33, v33, v41
	v_xor_b32_e32 v41, 16, v236
	v_cmp_lt_i32_e32 vcc, v41, v40
	s_nop 1
	v_cndmask_b32_e32 v41, v236, v41, vcc
	v_lshlrev_b32_e32 v41, 2, v41
	ds_bpermute_b32 v41, v41, v33
	s_waitcnt lgkmcnt(0)
	v_add_f32_e32 v33, v33, v41
	v_xor_b32_e32 v41, 32, v236
	v_cmp_lt_i32_e32 vcc, v41, v40
	s_nop 1
	v_cndmask_b32_e32 v40, v236, v41, vcc
	v_lshlrev_b32_e32 v40, 2, v40
	ds_bpermute_b32 v40, v40, v33
	s_waitcnt lgkmcnt(0)
	v_add_f32_e32 v33, v33, v40
	v_fmamk_f32 v33, v33, 0x3a800000, v233
	v_cmp_gt_f32_e32 vcc, s58, v33
	v_mul_f32_e32 v40, 0x4b800000, v33
	s_nop 0
	v_cndmask_b32_e32 v33, v33, v40, vcc
	v_rsq_f32_e32 v33, v33
	s_nop 0
	v_mul_f32_e32 v40, 0x45800000, v33
	v_cndmask_b32_e32 v40, v33, v40, vcc
	v_pk_mul_f32 v[4:5], v[4:5], v[40:41] op_sel_hi:[1,0]
	v_pk_mul_f32 v[6:7], v[6:7], v[40:41] op_sel_hi:[1,0]
	v_pk_mul_f32 v[0:1], v[0:1], v[4:5]
	v_pk_mul_f32 v[2:3], v[2:3], v[6:7]
	global_store_dwordx4 v[38:39], v[0:3], off
	v_cmp_lt_i32_e32 vcc, s62, v32
	s_or_b64 s[18:19], vcc, s[18:19]
	v_pk_mul_f32 v[0:1], v[12:13], v[40:41] op_sel_hi:[1,0]
	v_pk_mul_f32 v[2:3], v[14:15], v[40:41] op_sel_hi:[1,0]
	v_pk_mul_f32 v[0:1], v[8:9], v[0:1]
	v_pk_mul_f32 v[2:3], v[10:11], v[2:3]
	global_store_dwordx4 v[38:39], v[0:3], off offset:1024
	s_nop 1
	v_pk_mul_f32 v[0:1], v[20:21], v[40:41] op_sel_hi:[1,0]
	v_pk_mul_f32 v[2:3], v[22:23], v[40:41] op_sel_hi:[1,0]
	v_pk_mul_f32 v[0:1], v[16:17], v[0:1]
	v_pk_mul_f32 v[2:3], v[18:19], v[2:3]
	global_store_dwordx4 v[38:39], v[0:3], off offset:2048
	s_nop 1
	v_pk_mul_f32 v[0:1], v[24:25], v[40:41] op_sel_hi:[1,0]
	v_pk_mul_f32 v[2:3], v[26:27], v[40:41] op_sel_hi:[1,0]
	v_pk_mul_f32 v[0:1], v[28:29], v[0:1]
	v_pk_mul_f32 v[2:3], v[30:31], v[2:3]
	global_store_dwordx4 v[38:39], v[0:3], off offset:3072
	s_andn2_b64 exec, exec, s[18:19]
	s_cbranch_execnz .Lmy_fn_loop

; __global__ void __launch_bounds__(512) mega(Params pk) {
;     ...
;     for (int ph = ph_lo; ph < ph_hi; ++ph) {
;         const int l = (ph - 1) / 8, sub = (ph == 0) ? 9 : (((ph - 1) % 8) == 7 ? 8 : (ph - 1) % 8);
;         int nrep = 1;
;     ...
;         if (ph < N_PHASES - 1 && sub == (PROBE % 100)) nrep = 2;
;     ...
;         for (int rep = 0; rep < nrep; ++rep) {
;             const bool dry = (PROBE >= 200) && (rep == 0) && (nrep == 2);
;             if (ph == 0) { const Params p = load_params(lp); phase_prep(p, lds); }
;             else if (ph == N_PHASES - 1) { const Params p = load_params(lp); phase_final(p); }
;             else if (sub == 0 || sub == 5) { const Params p = load_params(lp); phase_norm(p, l, sub == 5); }
;             else if (sub == 2) { const Params p = load_params(lp); phase_mix(p, l, lds); }
;             else { for (int gi = 0; gi < 6; ++gi) { if (!gemm_phase(lds, l, sub, gi, dry)) break; } }
;             if (rep + 1 < nrep) xcd_barrier(xb);
;         }
;         if (ph + 1 < ph_hi) xcd_barrier(xb);
;         if (ph_hi > 1000) grid.sync();
;     }
.LBB0_735:
	s_cmpk_lg_u32 s72, 0x100
	s_cbranch_scc1 .Lmy_fn_nsk
	s_cmp_eq_u32 s16, 13
	s_cbranch_scc1 .Lmy_fn_sk
	s_cmp_eq_u32 s16, 16
	s_cbranch_scc1 .Lmy_fn_sk
	s_branch .Lmy_fn_nsk
.Lmy_fn_sk:
	s_add_i32 s16, s16, 1
.Lmy_fn_nsk:
	s_add_i32 s16, s16, 1
	v_readlane_b32 s0, v253, 4
	s_cmp_ge_i32 s16, s0
	s_cselect_b64 s[0:1], -1, 0
	s_and_b64 vcc, exec, s[0:1]
	v_readlane_b32 s15, v254, 63
	s_cbranch_vccnz .LBB0_789
	s_waitcnt vmcnt(0)
	s_waitcnt vmcnt(0) lgkmcnt(0)
	s_barrier
	s_mov_b64 s[18:19], exec
	v_readlane_b32 s4, v253, 2
	v_readlane_b32 s5, v253, 3
	s_and_b64 s[4:5], s[18:19], s[4:5]
	s_mov_b64 exec, s[4:5]
	s_cbranch_execz .LBB0_788
	v_readlane_b32 s2, v254, 51
	s_waitcnt vmcnt(0) expcnt(0) lgkmcnt(0)
	s_nop 0
	v_mov_b32_e32 v0, s2
	ds_read_b32 v2, v0
	v_readlane_b32 s2, v254, 52
	s_waitcnt lgkmcnt(0)
	v_cmp_ne_u32_e32 vcc, 0, v2
	v_mov_b32_e32 v0, s2
	ds_read_b32 v0, v0
	s_cbranch_vccnz .LBB0_752
	s_mov_b32 s2, 1
	s_branch .LBB0_740
